# sample attention loop: V fragments of the PV MFMAs double-buffered (second set in LDS-spilled constant VGPRs), counted lgkmcnt(8) waits
# baseline (speedup 1.0000x reference)
.LBB0_909:
	s_lshr_b32 s2, s67, 4
	s_ashr_i32 s42, s67, 7
	s_bfe_u32 s3, s2, 0x10002
	s_ashr_i32 s43, s42, 31
	s_lshl_b32 s2, s67, 8
	s_lshl_b64 s[4:5], s[42:43], 12
	s_and_b32 s2, s2, 0xf00
	s_bfe_u32 s10, s67, 0x30004
	s_or_b32 s2, s4, s2
	s_add_u32 s4, s2, 0x1000
	s_addc_u32 s5, s5, 0
	s_lshl_b32 s2, s42, 1
	s_or_b32 s11, s2, s3
	s_lshl_b64 s[44:45], s[4:5], 10
	s_mul_i32 s4, s4, 0xc00
	s_add_u32 s4, s4, 0x3000000
	s_add_u32 s4, s39, s4
	s_addc_u32 s5, s52, 0
	s_lshl_b32 s2, s10, 7
	s_lshl_b32 s10, s10, 8
	s_add_u32 s50, s4, s10
	s_addc_u32 s51, s5, 0
	s_mul_hi_u32 s4, s11, 0x110000
	s_mul_i32 s5, s43, 0x110000
	v_mov_b32_e32 v74, v204
	s_add_i32 s4, s4, s5
	s_mul_i32 s11, s11, 0x110000
	s_add_u32 s48, s61, s11
	s_waitcnt vmcnt(5)
	v_ashrrev_i32_e32 v16, 4, v74
	s_waitcnt vmcnt(4)
	v_lshlrev_b32_e32 v22, 3, v74
	v_add_u32_e32 v18, 32, v16
	s_addc_u32 s49, s62, s4
	s_waitcnt vmcnt(0)
	v_and_b32_e32 v0, 0x78, v22
	v_ashrrev_i32_e32 v17, 31, v16
	v_ashrrev_i32_e32 v19, 31, v18
	s_add_u32 s40, s63, s11
	v_lshlrev_b32_e32 v23, 1, v0
	s_waitcnt vmcnt(3)
	v_lshlrev_b64 v[48:49], 8, v[16:17]
	v_lshlrev_b64 v[12:13], 8, v[18:19]
	s_addc_u32 s41, s64, s4
	v_or_b32_e32 v50, v48, v23
	v_mov_b32_e32 v51, v49
	v_or_b32_e32 v12, v12, v23
	v_lshl_add_u64 v[0:1], s[40:41], 0, v[50:51]
	v_lshl_add_u64 v[4:5], s[40:41], 0, v[12:13]
	global_load_dwordx4 v[0:3], v[0:1], off
	s_nop 0
	global_load_dwordx4 v[4:7], v[4:5], off
	v_lshl_add_u64 v[8:9], s[48:49], 0, v[50:51]
	v_lshl_add_u64 v[12:13], s[48:49], 0, v[12:13]
	global_load_dwordx4 v[8:11], v[8:9], off
	v_ashrrev_i32_e32 v52, 1, v74
	global_load_dwordx4 v[12:15], v[12:13], off
	s_movk_i32 s4, 0xffe0
	v_bfi_b32 v20, s4, v52, v74
	v_ashrrev_i32_e32 v21, 31, v20
	v_bfe_u32 v186, v74, 5, 1
	v_mul_u32_u24_e32 v20, 0xc00, v20
	v_lshl_add_u64 v[20:21], s[50:51], 0, v[20:21]
	v_lshlrev_b32_e32 v96, 4, v186
	v_lshl_add_u64 v[20:21], v[20:21], 0, v[96:97]
	global_load_dwordx4 v[118:121], v[20:21], off
	global_load_dwordx4 v[114:117], v[20:21], off offset:32
	global_load_dwordx4 v[126:129], v[20:21], off offset:64
	global_load_dwordx4 v[122:125], v[20:21], off offset:96
	global_load_dwordx4 v[110:113], v[20:21], off offset:128
	global_load_dwordx4 v[106:109], v[20:21], off offset:160
	global_load_dwordx4 v[102:105], v[20:21], off offset:192
	global_load_dwordx4 v[98:101], v[20:21], off offset:224
	v_and_b32_e32 v19, 0xfffff0, v16
	v_lshlrev_b32_e32 v24, 1, v16
	v_lshrrev_b32_e32 v25, 1, v16
	v_and_b32_e32 v26, 3, v16
	v_and_or_b32 v19, v24, 8, v19
	v_and_or_b32 v24, v25, 4, v26
	v_and_b32_e32 v25, 0xfffff0, v18
	v_lshlrev_b32_e32 v26, 1, v18
	v_bfe_u32 v22, v22, 5, 2
	v_lshrrev_b32_e32 v19, 1, v19
	v_and_or_b32 v25, v26, 8, v25
	v_or_b32_e32 v19, v19, v22
	v_lshrrev_b32_e32 v25, 1, v25
	v_lshlrev_b32_e32 v24, 6, v24
	v_and_b32_e32 v27, 48, v23
	v_lshlrev_b32_e32 v19, 9, v19
	v_or_b32_e32 v22, v25, v22
	v_or3_b32 v19, v19, v24, v27
	v_lshlrev_b32_e32 v22, 9, v22
	v_or3_b32 v22, v22, v24, v27
	v_add_u32_e32 v192, 0, v19
	v_and_b32_e32 v17, 0x70, v74
	v_lshlrev_b32_e32 v16, 8, v16
	v_add_u32_e32 v193, 0, v22
	s_waitcnt vmcnt(0)
	v_bitop3_b32 v16, v23, v16, v17 bitop3:0xde
	v_and_b32_e32 v187, 31, v74
	v_lshlrev_b32_e32 v53, 4, v74
	v_add_u32_e32 v194, 0, v16
	s_add_i32 s5, 0, 0x10000
	s_mov_b64 s[10:11], 0x4000
	v_and_b32_e32 v182, 0xffffffe0, v52
	v_and_b32_e32 v75, 63, v74
	s_cmp_lg_u32 0, -1
	s_mul_i32 s4, s3, 0x110000
	s_waitcnt vmcnt(11)
	ds_write_b128 v192, v[0:3]
	s_waitcnt vmcnt(10)
	ds_write_b128 v193, v[4:7]
	v_lshlrev_b32_e32 v0, 8, v18
	v_bitop3_b32 v0, v23, v0, v17 bitop3:0xde
	v_add_u32_e32 v195, 0, v0
	s_waitcnt vmcnt(9)
	ds_write_b128 v194, v[8:11] offset:32768
	s_waitcnt vmcnt(8)
	ds_write_b128 v195, v[12:15] offset:32768
	s_load_dwordx2 s[100:101], s[88:89], 0x80
	v_lshlrev_b32_e32 v175, 5, v186
	v_mov_b32_e32 v188, s44
	v_lshrrev_b32_e32 v188, 10, v188
	v_lshrrev_b32_e32 v189, 1, v74
	v_and_b32_e32 v189, 0xffe0, v189
	v_and_or_b32 v189, v74, 31, v189
	v_add_u32_e32 v188, v188, v189
	v_bfe_u32 v94, v188, 6, 6
	v_and_b32_e32 v95, 63, v188
	v_cvt_f32_ubyte0_e32 v94, v94
	v_cvt_f32_ubyte0_e32 v95, v95
	v_lshlrev_b32_e32 v190, 4, v186
	v_add_u32_e32 v191, 0, v190
	v_cvt_f32_ubyte0_e32 v78, v191
	v_add_u32_e32 v191, 2, v190
	v_cvt_f32_ubyte0_e32 v79, v191
	v_add_u32_e32 v191, 4, v190
	v_cvt_f32_ubyte0_e32 v80, v191
	v_add_u32_e32 v191, 6, v190
	v_cvt_f32_ubyte0_e32 v81, v191
	v_add_u32_e32 v191, 8, v190
	v_cvt_f32_ubyte0_e32 v82, v191
	v_add_u32_e32 v191, 10, v190
	v_cvt_f32_ubyte0_e32 v83, v191
	v_add_u32_e32 v191, 12, v190
	v_cvt_f32_ubyte0_e32 v84, v191
	v_add_u32_e32 v191, 14, v190
	v_cvt_f32_ubyte0_e32 v85, v191
	v_add_u32_e32 v191, 32, v190
	v_cvt_f32_ubyte0_e32 v86, v191
	v_add_u32_e32 v191, 34, v190
	v_cvt_f32_ubyte0_e32 v87, v191
	v_add_u32_e32 v191, 36, v190
	v_cvt_f32_ubyte0_e32 v88, v191
	v_add_u32_e32 v191, 38, v190
	v_cvt_f32_ubyte0_e32 v89, v191
	v_add_u32_e32 v191, 40, v190
	v_cvt_f32_ubyte0_e32 v90, v191
	v_add_u32_e32 v191, 42, v190
	v_cvt_f32_ubyte0_e32 v91, v191
	v_add_u32_e32 v191, 44, v190
	v_cvt_f32_ubyte0_e32 v92, v191
	v_add_u32_e32 v191, 46, v190
	v_cvt_f32_ubyte0_e32 v93, v191
	v_mul_f32_e32 v78, 0xbe549a78, v78
	v_mul_f32_e32 v79, 0xbe549a78, v79
	v_mul_f32_e32 v80, 0xbe549a78, v80
	v_mul_f32_e32 v81, 0xbe549a78, v81
	v_mul_f32_e32 v82, 0xbe549a78, v82
	v_mul_f32_e32 v83, 0xbe549a78, v83
	v_mul_f32_e32 v84, 0xbe549a78, v84
	v_mul_f32_e32 v85, 0xbe549a78, v85
	v_mul_f32_e32 v86, 0xbe549a78, v86
	v_mul_f32_e32 v87, 0xbe549a78, v87
	v_mul_f32_e32 v88, 0xbe549a78, v88
	v_mul_f32_e32 v89, 0xbe549a78, v89
	v_mul_f32_e32 v90, 0xbe549a78, v90
	v_mul_f32_e32 v91, 0xbe549a78, v91
	v_mul_f32_e32 v92, 0xbe549a78, v92
	v_mul_f32_e32 v93, 0xbe549a78, v93
	v_exp_f32_e32 v78, v78
	v_exp_f32_e32 v79, v79
	v_exp_f32_e32 v80, v80
	v_exp_f32_e32 v81, v81
	v_exp_f32_e32 v82, v82
	v_exp_f32_e32 v83, v83
	v_exp_f32_e32 v84, v84
	v_exp_f32_e32 v85, v85
	v_exp_f32_e32 v86, v86
	v_exp_f32_e32 v87, v87
	v_exp_f32_e32 v88, v88
	v_exp_f32_e32 v89, v89
	v_exp_f32_e32 v90, v90
	v_exp_f32_e32 v91, v91
	v_exp_f32_e32 v92, v92
	v_exp_f32_e32 v93, v93
	s_waitcnt lgkmcnt(0)
	global_load_dwordx4 v[130:133], v175, s[100:101] offset:0
	global_load_dwordx4 v[134:137], v175, s[100:101] offset:16
	global_load_dwordx4 v[138:141], v175, s[100:101] offset:64
	global_load_dwordx4 v[142:145], v175, s[100:101] offset:80
	global_load_dwordx4 v[146:149], v175, s[100:101] offset:128
	global_load_dwordx4 v[150:153], v175, s[100:101] offset:144
	global_load_dwordx4 v[154:157], v175, s[100:101] offset:192
	global_load_dwordx4 v[158:161], v175, s[100:101] offset:208
	global_load_dwordx4 v[224:227], v175, s[100:101] offset:256
	global_load_dwordx4 v[228:231], v175, s[100:101] offset:272
	global_load_dwordx4 v[232:235], v175, s[100:101] offset:320
	global_load_dwordx4 v[236:239], v175, s[100:101] offset:336
	global_load_dwordx4 v[240:243], v175, s[100:101] offset:384
	global_load_dwordx4 v[244:247], v175, s[100:101] offset:400
	global_load_dwordx4 v[248:251], v175, s[100:101] offset:448
	global_load_dwordx4 v[164:167], v175, s[100:101] offset:464
	v_lshlrev_b32_e32 v24, 16, v118
	v_and_b32_e32 v25, 0xffff0000, v118
	v_lshlrev_b32_e32 v26, 16, v119
	v_and_b32_e32 v27, 0xffff0000, v119
	v_lshlrev_b32_e32 v28, 16, v120
	v_and_b32_e32 v29, 0xffff0000, v120
	v_lshlrev_b32_e32 v30, 16, v121
	v_and_b32_e32 v31, 0xffff0000, v121
	v_mul_f32_e32 v168, v24, v24
	v_fmac_f32_e32 v168, v25, v25
	v_fmac_f32_e32 v168, v26, v26
	v_fmac_f32_e32 v168, v27, v27
	v_fmac_f32_e32 v168, v28, v28
	v_fmac_f32_e32 v168, v29, v29
	v_fmac_f32_e32 v168, v30, v30
	v_fmac_f32_e32 v168, v31, v31
	v_lshlrev_b32_e32 v24, 16, v114
	v_and_b32_e32 v25, 0xffff0000, v114
	v_lshlrev_b32_e32 v26, 16, v115
	v_and_b32_e32 v27, 0xffff0000, v115
	v_lshlrev_b32_e32 v28, 16, v116
	v_and_b32_e32 v29, 0xffff0000, v116
	v_lshlrev_b32_e32 v30, 16, v117
	v_and_b32_e32 v31, 0xffff0000, v117
	v_fmac_f32_e32 v168, v24, v24
	v_fmac_f32_e32 v168, v25, v25
	v_fmac_f32_e32 v168, v26, v26
	v_fmac_f32_e32 v168, v27, v27
	v_fmac_f32_e32 v168, v28, v28
	v_fmac_f32_e32 v168, v29, v29
	v_fmac_f32_e32 v168, v30, v30
	v_fmac_f32_e32 v168, v31, v31
	v_lshlrev_b32_e32 v24, 16, v126
	v_and_b32_e32 v25, 0xffff0000, v126
	v_lshlrev_b32_e32 v26, 16, v127
	v_and_b32_e32 v27, 0xffff0000, v127
	v_lshlrev_b32_e32 v28, 16, v128
	v_and_b32_e32 v29, 0xffff0000, v128
	v_lshlrev_b32_e32 v30, 16, v129
	v_and_b32_e32 v31, 0xffff0000, v129
	v_fmac_f32_e32 v168, v24, v24
	v_fmac_f32_e32 v168, v25, v25
	v_fmac_f32_e32 v168, v26, v26
	v_fmac_f32_e32 v168, v27, v27
	v_fmac_f32_e32 v168, v28, v28
	v_fmac_f32_e32 v168, v29, v29
	v_fmac_f32_e32 v168, v30, v30
	v_fmac_f32_e32 v168, v31, v31
	v_lshlrev_b32_e32 v24, 16, v122
	v_and_b32_e32 v25, 0xffff0000, v122
	v_lshlrev_b32_e32 v26, 16, v123
	v_and_b32_e32 v27, 0xffff0000, v123
	v_lshlrev_b32_e32 v28, 16, v124
	v_and_b32_e32 v29, 0xffff0000, v124
	v_lshlrev_b32_e32 v30, 16, v125
	v_and_b32_e32 v31, 0xffff0000, v125
	v_fmac_f32_e32 v168, v24, v24
	v_fmac_f32_e32 v168, v25, v25
	v_fmac_f32_e32 v168, v26, v26
	v_fmac_f32_e32 v168, v27, v27
	v_fmac_f32_e32 v168, v28, v28
	v_fmac_f32_e32 v168, v29, v29
	v_fmac_f32_e32 v168, v30, v30
	v_fmac_f32_e32 v168, v31, v31
	v_lshlrev_b32_e32 v24, 16, v110
	v_and_b32_e32 v25, 0xffff0000, v110
	v_lshlrev_b32_e32 v26, 16, v111
	v_and_b32_e32 v27, 0xffff0000, v111
	v_lshlrev_b32_e32 v28, 16, v112
	v_and_b32_e32 v29, 0xffff0000, v112
	v_lshlrev_b32_e32 v30, 16, v113
	v_and_b32_e32 v31, 0xffff0000, v113
	v_fmac_f32_e32 v168, v24, v24
	v_fmac_f32_e32 v168, v25, v25
	v_fmac_f32_e32 v168, v26, v26
	v_fmac_f32_e32 v168, v27, v27
	v_fmac_f32_e32 v168, v28, v28
	v_fmac_f32_e32 v168, v29, v29
	v_fmac_f32_e32 v168, v30, v30
	v_fmac_f32_e32 v168, v31, v31
	v_lshlrev_b32_e32 v24, 16, v106
	v_and_b32_e32 v25, 0xffff0000, v106
	v_lshlrev_b32_e32 v26, 16, v107
	v_and_b32_e32 v27, 0xffff0000, v107
	v_lshlrev_b32_e32 v28, 16, v108
	v_and_b32_e32 v29, 0xffff0000, v108
	v_lshlrev_b32_e32 v30, 16, v109
	v_and_b32_e32 v31, 0xffff0000, v109
	v_fmac_f32_e32 v168, v24, v24
	v_fmac_f32_e32 v168, v25, v25
	v_fmac_f32_e32 v168, v26, v26
	v_fmac_f32_e32 v168, v27, v27
	v_fmac_f32_e32 v168, v28, v28
	v_fmac_f32_e32 v168, v29, v29
	v_fmac_f32_e32 v168, v30, v30
	v_fmac_f32_e32 v168, v31, v31
	v_lshlrev_b32_e32 v24, 16, v102
	v_and_b32_e32 v25, 0xffff0000, v102
	v_lshlrev_b32_e32 v26, 16, v103
	v_and_b32_e32 v27, 0xffff0000, v103
	v_lshlrev_b32_e32 v28, 16, v104
	v_and_b32_e32 v29, 0xffff0000, v104
	v_lshlrev_b32_e32 v30, 16, v105
	v_and_b32_e32 v31, 0xffff0000, v105
	v_fmac_f32_e32 v168, v24, v24
	v_fmac_f32_e32 v168, v25, v25
	v_fmac_f32_e32 v168, v26, v26
	v_fmac_f32_e32 v168, v27, v27
	v_fmac_f32_e32 v168, v28, v28
	v_fmac_f32_e32 v168, v29, v29
	v_fmac_f32_e32 v168, v30, v30
	v_fmac_f32_e32 v168, v31, v31
	v_lshlrev_b32_e32 v24, 16, v98
	v_and_b32_e32 v25, 0xffff0000, v98
	v_lshlrev_b32_e32 v26, 16, v99
	v_and_b32_e32 v27, 0xffff0000, v99
	v_lshlrev_b32_e32 v28, 16, v100
	v_and_b32_e32 v29, 0xffff0000, v100
	v_lshlrev_b32_e32 v30, 16, v101
	v_and_b32_e32 v31, 0xffff0000, v101
	v_fmac_f32_e32 v168, v24, v24
	v_fmac_f32_e32 v168, v25, v25
	v_fmac_f32_e32 v168, v26, v26
	v_fmac_f32_e32 v168, v27, v27
	v_fmac_f32_e32 v168, v28, v28
	v_fmac_f32_e32 v168, v29, v29
	v_fmac_f32_e32 v168, v30, v30
	v_fmac_f32_e32 v168, v31, v31
	v_mov_b32_e32 v170, v168
	s_nop 1
	v_permlane32_swap_b32_e32 v168, v170
	v_add_f32_e32 v168, v168, v170
	v_fmamk_f32 v168, v168, 0x3c000000, v207
	v_rsq_f32_e32 v169, v168
	s_nop 0
	v_mul_f32_e32 v170, v168, v169
	v_fma_f32 v170, -v170, v169, 1.0
	v_mul_f32_e32 v170, 0.5, v170
	v_fmac_f32_e32 v169, v169, v170
	s_waitcnt vmcnt(0)
	v_lshlrev_b32_e32 v24, 16, v118
	v_and_b32_e32 v25, 0xffff0000, v118
	v_lshlrev_b32_e32 v26, 16, v119
	v_and_b32_e32 v27, 0xffff0000, v119
	v_lshlrev_b32_e32 v28, 16, v120
	v_and_b32_e32 v29, 0xffff0000, v120
	v_lshlrev_b32_e32 v30, 16, v121
	v_and_b32_e32 v31, 0xffff0000, v121
	v_lshlrev_b32_e32 v34, 16, v126
	v_and_b32_e32 v35, 0xffff0000, v126
	v_lshlrev_b32_e32 v36, 16, v127
	v_and_b32_e32 v37, 0xffff0000, v127
	v_lshlrev_b32_e32 v38, 16, v128
	v_and_b32_e32 v39, 0xffff0000, v128
	v_lshlrev_b32_e32 v40, 16, v129
	v_and_b32_e32 v41, 0xffff0000, v129
	v_mul_f32_e32 v24, v24, v169
	v_mul_f32_e32 v25, v25, v169
	v_mul_f32_e32 v26, v26, v169
	v_mul_f32_e32 v27, v27, v169
	v_mul_f32_e32 v28, v28, v169
	v_mul_f32_e32 v29, v29, v169
	v_mul_f32_e32 v30, v30, v169
	v_mul_f32_e32 v31, v31, v169
	v_mul_f32_e32 v24, v24, v130
	v_mul_f32_e32 v25, v25, v131
	v_mul_f32_e32 v26, v26, v132
	v_mul_f32_e32 v27, v27, v133
	v_mul_f32_e32 v28, v28, v134
	v_mul_f32_e32 v29, v29, v135
	v_mul_f32_e32 v30, v30, v136
	v_mul_f32_e32 v31, v31, v137
	v_mul_f32_e32 v34, v34, v169
	v_mul_f32_e32 v35, v35, v169
	v_mul_f32_e32 v36, v36, v169
	v_mul_f32_e32 v37, v37, v169
	v_mul_f32_e32 v38, v38, v169
	v_mul_f32_e32 v39, v39, v169
	v_mul_f32_e32 v40, v40, v169
	v_mul_f32_e32 v41, v41, v169
	v_mul_f32_e32 v34, v34, v146
	v_mul_f32_e32 v35, v35, v147
	v_mul_f32_e32 v36, v36, v148
	v_mul_f32_e32 v37, v37, v149
	v_mul_f32_e32 v38, v38, v150
	v_mul_f32_e32 v39, v39, v151
	v_mul_f32_e32 v40, v40, v152
	v_mul_f32_e32 v41, v41, v153
	v_mul_f32_e32 v60, v78, v94
	v_mul_f32_e32 v61, v79, v94
	v_mul_f32_e32 v62, v80, v94
	v_mul_f32_e32 v63, v81, v94
	v_mul_f32_e32 v64, v82, v94
	v_mul_f32_e32 v65, v83, v94
	v_mul_f32_e32 v66, v84, v94
	v_mul_f32_e32 v67, v85, v94
	v_mul_f32_e32 v68, 0.15915494, v60
	v_mul_f32_e32 v69, 0.15915494, v61
	v_mul_f32_e32 v70, 0.15915494, v62
	v_mul_f32_e32 v71, 0.15915494, v63
	v_mul_f32_e32 v72, 0.15915494, v64
	v_mul_f32_e32 v73, 0.15915494, v65
	v_mul_f32_e32 v76, 0.15915494, v66
	v_mul_f32_e32 v77, 0.15915494, v67
	v_rndne_f32_e32 v68, v68
	v_rndne_f32_e32 v69, v69
	v_rndne_f32_e32 v70, v70
	v_rndne_f32_e32 v71, v71
	v_rndne_f32_e32 v72, v72
	v_rndne_f32_e32 v73, v73
	v_rndne_f32_e32 v76, v76
	v_rndne_f32_e32 v77, v77
	v_fmac_f32_e32 v60, 0xc0c90fdb, v68
	v_fmac_f32_e32 v61, 0xc0c90fdb, v69
	v_fmac_f32_e32 v62, 0xc0c90fdb, v70
	v_fmac_f32_e32 v63, 0xc0c90fdb, v71
	v_fmac_f32_e32 v64, 0xc0c90fdb, v72
	v_fmac_f32_e32 v65, 0xc0c90fdb, v73
	v_fmac_f32_e32 v66, 0xc0c90fdb, v76
	v_fmac_f32_e32 v67, 0xc0c90fdb, v77
	v_fmac_f32_e32 v60, 0x343bbd2e, v68
	v_fmac_f32_e32 v61, 0x343bbd2e, v69
	v_fmac_f32_e32 v62, 0x343bbd2e, v70
	v_fmac_f32_e32 v63, 0x343bbd2e, v71
	v_fmac_f32_e32 v64, 0x343bbd2e, v72
	v_fmac_f32_e32 v65, 0x343bbd2e, v73
	v_fmac_f32_e32 v66, 0x343bbd2e, v76
	v_fmac_f32_e32 v67, 0x343bbd2e, v77
	v_mul_f32_e32 v60, 0.15915494, v60
	v_mul_f32_e32 v61, 0.15915494, v61
	v_mul_f32_e32 v62, 0.15915494, v62
	v_mul_f32_e32 v63, 0.15915494, v63
	v_mul_f32_e32 v64, 0.15915494, v64
	v_mul_f32_e32 v65, 0.15915494, v65
	v_mul_f32_e32 v66, 0.15915494, v66
	v_mul_f32_e32 v67, 0.15915494, v67
	v_sin_f32_e32 v68, v60
	v_sin_f32_e32 v69, v61
	v_sin_f32_e32 v70, v62
	v_sin_f32_e32 v71, v63
	v_sin_f32_e32 v72, v64
	v_sin_f32_e32 v73, v65
	v_sin_f32_e32 v76, v66
	v_sin_f32_e32 v77, v67
	v_cos_f32_e32 v60, v60
	v_cos_f32_e32 v61, v61
	v_cos_f32_e32 v62, v62
	v_cos_f32_e32 v63, v63
	v_cos_f32_e32 v64, v64
	v_cos_f32_e32 v65, v65
	v_cos_f32_e32 v66, v66
	v_cos_f32_e32 v67, v67
	s_nop 0
	v_mul_f32_e32 v171, v68, v34
	v_mul_f32_e32 v172, v60, v34
	v_fmac_f32_e32 v172, v68, v24
	v_fma_f32 v24, v60, v24, -v171
	v_mov_b32_e32 v34, v172
	v_mul_f32_e32 v171, v69, v35
	v_mul_f32_e32 v172, v61, v35
	v_fmac_f32_e32 v172, v69, v25
	v_fma_f32 v25, v61, v25, -v171
	v_mov_b32_e32 v35, v172
	v_mul_f32_e32 v171, v70, v36
	v_mul_f32_e32 v172, v62, v36
	v_fmac_f32_e32 v172, v70, v26
	v_fma_f32 v26, v62, v26, -v171
	v_mov_b32_e32 v36, v172
	v_mul_f32_e32 v171, v71, v37
	v_mul_f32_e32 v172, v63, v37
	v_fmac_f32_e32 v172, v71, v27
	v_fma_f32 v27, v63, v27, -v171
	v_mov_b32_e32 v37, v172
	v_mul_f32_e32 v171, v72, v38
	v_mul_f32_e32 v172, v64, v38
	v_fmac_f32_e32 v172, v72, v28
	v_fma_f32 v28, v64, v28, -v171
	v_mov_b32_e32 v38, v172
	v_mul_f32_e32 v171, v73, v39
	v_mul_f32_e32 v172, v65, v39
	v_fmac_f32_e32 v172, v73, v29
	v_fma_f32 v29, v65, v29, -v171
	v_mov_b32_e32 v39, v172
	v_mul_f32_e32 v171, v76, v40
	v_mul_f32_e32 v172, v66, v40
	v_fmac_f32_e32 v172, v76, v30
	v_fma_f32 v30, v66, v30, -v171
	v_mov_b32_e32 v40, v172
	v_mul_f32_e32 v171, v77, v41
	v_mul_f32_e32 v172, v67, v41
	v_fmac_f32_e32 v172, v77, v31
	v_fma_f32 v31, v67, v31, -v171
	v_mov_b32_e32 v41, v172
	v_cvt_pk_bf16_f32 v118, v24, v25
	v_cvt_pk_bf16_f32 v119, v26, v27
	v_cvt_pk_bf16_f32 v120, v28, v29
	v_cvt_pk_bf16_f32 v121, v30, v31
	v_cvt_pk_bf16_f32 v126, v34, v35
	v_cvt_pk_bf16_f32 v127, v36, v37
	v_cvt_pk_bf16_f32 v128, v38, v39
	v_cvt_pk_bf16_f32 v129, v40, v41
	v_lshlrev_b32_e32 v24, 16, v114
	v_and_b32_e32 v25, 0xffff0000, v114
	v_lshlrev_b32_e32 v26, 16, v115
	v_and_b32_e32 v27, 0xffff0000, v115
	v_lshlrev_b32_e32 v28, 16, v116
	v_and_b32_e32 v29, 0xffff0000, v116
	v_lshlrev_b32_e32 v30, 16, v117
	v_and_b32_e32 v31, 0xffff0000, v117
	v_lshlrev_b32_e32 v34, 16, v122
	v_and_b32_e32 v35, 0xffff0000, v122
	v_lshlrev_b32_e32 v36, 16, v123
	v_and_b32_e32 v37, 0xffff0000, v123
	v_lshlrev_b32_e32 v38, 16, v124
	v_and_b32_e32 v39, 0xffff0000, v124
	v_lshlrev_b32_e32 v40, 16, v125
	v_and_b32_e32 v41, 0xffff0000, v125
	v_mul_f32_e32 v24, v24, v169
	v_mul_f32_e32 v25, v25, v169
	v_mul_f32_e32 v26, v26, v169
	v_mul_f32_e32 v27, v27, v169
	v_mul_f32_e32 v28, v28, v169
	v_mul_f32_e32 v29, v29, v169
	v_mul_f32_e32 v30, v30, v169
	v_mul_f32_e32 v31, v31, v169
	v_mul_f32_e32 v24, v24, v138
	v_mul_f32_e32 v25, v25, v139
	v_mul_f32_e32 v26, v26, v140
	v_mul_f32_e32 v27, v27, v141
	v_mul_f32_e32 v28, v28, v142
	v_mul_f32_e32 v29, v29, v143
	v_mul_f32_e32 v30, v30, v144
	v_mul_f32_e32 v31, v31, v145
	v_mul_f32_e32 v34, v34, v169
	v_mul_f32_e32 v35, v35, v169
	v_mul_f32_e32 v36, v36, v169
	v_mul_f32_e32 v37, v37, v169
	v_mul_f32_e32 v38, v38, v169
	v_mul_f32_e32 v39, v39, v169
	v_mul_f32_e32 v40, v40, v169
	v_mul_f32_e32 v41, v41, v169
	v_mul_f32_e32 v34, v34, v154
	v_mul_f32_e32 v35, v35, v155
	v_mul_f32_e32 v36, v36, v156
	v_mul_f32_e32 v37, v37, v157
	v_mul_f32_e32 v38, v38, v158
	v_mul_f32_e32 v39, v39, v159
	v_mul_f32_e32 v40, v40, v160
	v_mul_f32_e32 v41, v41, v161
	v_mul_f32_e32 v60, v86, v94
	v_mul_f32_e32 v61, v87, v94
	v_mul_f32_e32 v62, v88, v94
	v_mul_f32_e32 v63, v89, v94
	v_mul_f32_e32 v64, v90, v94
	v_mul_f32_e32 v65, v91, v94
	v_mul_f32_e32 v66, v92, v94
	v_mul_f32_e32 v67, v93, v94
	v_mul_f32_e32 v68, 0.15915494, v60
	v_mul_f32_e32 v69, 0.15915494, v61
	v_mul_f32_e32 v70, 0.15915494, v62
	v_mul_f32_e32 v71, 0.15915494, v63
	v_mul_f32_e32 v72, 0.15915494, v64
	v_mul_f32_e32 v73, 0.15915494, v65
	v_mul_f32_e32 v76, 0.15915494, v66
	v_mul_f32_e32 v77, 0.15915494, v67
	v_rndne_f32_e32 v68, v68
	v_rndne_f32_e32 v69, v69
	v_rndne_f32_e32 v70, v70
	v_rndne_f32_e32 v71, v71
	v_rndne_f32_e32 v72, v72
	v_rndne_f32_e32 v73, v73
	v_rndne_f32_e32 v76, v76
	v_rndne_f32_e32 v77, v77
	v_fmac_f32_e32 v60, 0xc0c90fdb, v68
	v_fmac_f32_e32 v61, 0xc0c90fdb, v69
	v_fmac_f32_e32 v62, 0xc0c90fdb, v70
	v_fmac_f32_e32 v63, 0xc0c90fdb, v71
	v_fmac_f32_e32 v64, 0xc0c90fdb, v72
	v_fmac_f32_e32 v65, 0xc0c90fdb, v73
	v_fmac_f32_e32 v66, 0xc0c90fdb, v76
	v_fmac_f32_e32 v67, 0xc0c90fdb, v77
	v_fmac_f32_e32 v60, 0x343bbd2e, v68
	v_fmac_f32_e32 v61, 0x343bbd2e, v69
	v_fmac_f32_e32 v62, 0x343bbd2e, v70
	v_fmac_f32_e32 v63, 0x343bbd2e, v71
	v_fmac_f32_e32 v64, 0x343bbd2e, v72
	v_fmac_f32_e32 v65, 0x343bbd2e, v73
	v_fmac_f32_e32 v66, 0x343bbd2e, v76
	v_fmac_f32_e32 v67, 0x343bbd2e, v77
	v_mul_f32_e32 v60, 0.15915494, v60
	v_mul_f32_e32 v61, 0.15915494, v61
	v_mul_f32_e32 v62, 0.15915494, v62
	v_mul_f32_e32 v63, 0.15915494, v63
	v_mul_f32_e32 v64, 0.15915494, v64
	v_mul_f32_e32 v65, 0.15915494, v65
	v_mul_f32_e32 v66, 0.15915494, v66
	v_mul_f32_e32 v67, 0.15915494, v67
	v_sin_f32_e32 v68, v60
	v_sin_f32_e32 v69, v61
	v_sin_f32_e32 v70, v62
	v_sin_f32_e32 v71, v63
	v_sin_f32_e32 v72, v64
	v_sin_f32_e32 v73, v65
	v_sin_f32_e32 v76, v66
	v_sin_f32_e32 v77, v67
	v_cos_f32_e32 v60, v60
	v_cos_f32_e32 v61, v61
	v_cos_f32_e32 v62, v62
	v_cos_f32_e32 v63, v63
	v_cos_f32_e32 v64, v64
	v_cos_f32_e32 v65, v65
	v_cos_f32_e32 v66, v66
	v_cos_f32_e32 v67, v67
	s_nop 0
	v_mul_f32_e32 v171, v68, v34
	v_mul_f32_e32 v172, v60, v34
	v_fmac_f32_e32 v172, v68, v24
	v_fma_f32 v24, v60, v24, -v171
	v_mov_b32_e32 v34, v172
	v_mul_f32_e32 v171, v69, v35
	v_mul_f32_e32 v172, v61, v35
	v_fmac_f32_e32 v172, v69, v25
	v_fma_f32 v25, v61, v25, -v171
	v_mov_b32_e32 v35, v172
	v_mul_f32_e32 v171, v70, v36
	v_mul_f32_e32 v172, v62, v36
	v_fmac_f32_e32 v172, v70, v26
	v_fma_f32 v26, v62, v26, -v171
	v_mov_b32_e32 v36, v172
	v_mul_f32_e32 v171, v71, v37
	v_mul_f32_e32 v172, v63, v37
	v_fmac_f32_e32 v172, v71, v27
	v_fma_f32 v27, v63, v27, -v171
	v_mov_b32_e32 v37, v172
	v_mul_f32_e32 v171, v72, v38
	v_mul_f32_e32 v172, v64, v38
	v_fmac_f32_e32 v172, v72, v28
	v_fma_f32 v28, v64, v28, -v171
	v_mov_b32_e32 v38, v172
	v_mul_f32_e32 v171, v73, v39
	v_mul_f32_e32 v172, v65, v39
	v_fmac_f32_e32 v172, v73, v29
	v_fma_f32 v29, v65, v29, -v171
	v_mov_b32_e32 v39, v172
	v_mul_f32_e32 v171, v76, v40
	v_mul_f32_e32 v172, v66, v40
	v_fmac_f32_e32 v172, v76, v30
	v_fma_f32 v30, v66, v30, -v171
	v_mov_b32_e32 v40, v172
	v_mul_f32_e32 v171, v77, v41
	v_mul_f32_e32 v172, v67, v41
	v_fmac_f32_e32 v172, v77, v31
	v_fma_f32 v31, v67, v31, -v171
	v_mov_b32_e32 v41, v172
	v_cvt_pk_bf16_f32 v114, v24, v25
	v_cvt_pk_bf16_f32 v115, v26, v27
	v_cvt_pk_bf16_f32 v116, v28, v29
	v_cvt_pk_bf16_f32 v117, v30, v31
	v_cvt_pk_bf16_f32 v122, v34, v35
	v_cvt_pk_bf16_f32 v123, v36, v37
	v_cvt_pk_bf16_f32 v124, v38, v39
	v_cvt_pk_bf16_f32 v125, v40, v41
	v_lshlrev_b32_e32 v24, 16, v110
	v_and_b32_e32 v25, 0xffff0000, v110
	v_lshlrev_b32_e32 v26, 16, v111
	v_and_b32_e32 v27, 0xffff0000, v111
	v_lshlrev_b32_e32 v28, 16, v112
	v_and_b32_e32 v29, 0xffff0000, v112
	v_lshlrev_b32_e32 v30, 16, v113
	v_and_b32_e32 v31, 0xffff0000, v113
	v_lshlrev_b32_e32 v34, 16, v102
	v_and_b32_e32 v35, 0xffff0000, v102
	v_lshlrev_b32_e32 v36, 16, v103
	v_and_b32_e32 v37, 0xffff0000, v103
	v_lshlrev_b32_e32 v38, 16, v104
	v_and_b32_e32 v39, 0xffff0000, v104
	v_lshlrev_b32_e32 v40, 16, v105
	v_and_b32_e32 v41, 0xffff0000, v105
	v_mul_f32_e32 v24, v24, v169
	v_mul_f32_e32 v25, v25, v169
	v_mul_f32_e32 v26, v26, v169
	v_mul_f32_e32 v27, v27, v169
	v_mul_f32_e32 v28, v28, v169
	v_mul_f32_e32 v29, v29, v169
	v_mul_f32_e32 v30, v30, v169
	v_mul_f32_e32 v31, v31, v169
	v_mul_f32_e32 v24, v24, v224
	v_mul_f32_e32 v25, v25, v225
	v_mul_f32_e32 v26, v26, v226
	v_mul_f32_e32 v27, v27, v227
	v_mul_f32_e32 v28, v28, v228
	v_mul_f32_e32 v29, v29, v229
	v_mul_f32_e32 v30, v30, v230
	v_mul_f32_e32 v31, v31, v231
	v_mul_f32_e32 v34, v34, v169
	v_mul_f32_e32 v35, v35, v169
	v_mul_f32_e32 v36, v36, v169
	v_mul_f32_e32 v37, v37, v169
	v_mul_f32_e32 v38, v38, v169
	v_mul_f32_e32 v39, v39, v169
	v_mul_f32_e32 v40, v40, v169
	v_mul_f32_e32 v41, v41, v169
	v_mul_f32_e32 v34, v34, v240
	v_mul_f32_e32 v35, v35, v241
	v_mul_f32_e32 v36, v36, v242
	v_mul_f32_e32 v37, v37, v243
	v_mul_f32_e32 v38, v38, v244
	v_mul_f32_e32 v39, v39, v245
	v_mul_f32_e32 v40, v40, v246
	v_mul_f32_e32 v41, v41, v247
	v_mul_f32_e32 v60, v78, v95
	v_mul_f32_e32 v61, v79, v95
	v_mul_f32_e32 v62, v80, v95
	v_mul_f32_e32 v63, v81, v95
	v_mul_f32_e32 v64, v82, v95
	v_mul_f32_e32 v65, v83, v95
	v_mul_f32_e32 v66, v84, v95
	v_mul_f32_e32 v67, v85, v95
	v_mul_f32_e32 v68, 0.15915494, v60
	v_mul_f32_e32 v69, 0.15915494, v61
	v_mul_f32_e32 v70, 0.15915494, v62
	v_mul_f32_e32 v71, 0.15915494, v63
	v_mul_f32_e32 v72, 0.15915494, v64
	v_mul_f32_e32 v73, 0.15915494, v65
	v_mul_f32_e32 v76, 0.15915494, v66
	v_mul_f32_e32 v77, 0.15915494, v67
	v_rndne_f32_e32 v68, v68
	v_rndne_f32_e32 v69, v69
	v_rndne_f32_e32 v70, v70
	v_rndne_f32_e32 v71, v71
	v_rndne_f32_e32 v72, v72
	v_rndne_f32_e32 v73, v73
	v_rndne_f32_e32 v76, v76
	v_rndne_f32_e32 v77, v77
	v_fmac_f32_e32 v60, 0xc0c90fdb, v68
	v_fmac_f32_e32 v61, 0xc0c90fdb, v69
	v_fmac_f32_e32 v62, 0xc0c90fdb, v70
	v_fmac_f32_e32 v63, 0xc0c90fdb, v71
	v_fmac_f32_e32 v64, 0xc0c90fdb, v72
	v_fmac_f32_e32 v65, 0xc0c90fdb, v73
	v_fmac_f32_e32 v66, 0xc0c90fdb, v76
	v_fmac_f32_e32 v67, 0xc0c90fdb, v77
	v_fmac_f32_e32 v60, 0x343bbd2e, v68
	v_fmac_f32_e32 v61, 0x343bbd2e, v69
	v_fmac_f32_e32 v62, 0x343bbd2e, v70
	v_fmac_f32_e32 v63, 0x343bbd2e, v71
	v_fmac_f32_e32 v64, 0x343bbd2e, v72
	v_fmac_f32_e32 v65, 0x343bbd2e, v73
	v_fmac_f32_e32 v66, 0x343bbd2e, v76
	v_fmac_f32_e32 v67, 0x343bbd2e, v77
	v_mul_f32_e32 v60, 0.15915494, v60
	v_mul_f32_e32 v61, 0.15915494, v61
	v_mul_f32_e32 v62, 0.15915494, v62
	v_mul_f32_e32 v63, 0.15915494, v63
	v_mul_f32_e32 v64, 0.15915494, v64
	v_mul_f32_e32 v65, 0.15915494, v65
	v_mul_f32_e32 v66, 0.15915494, v66
	v_mul_f32_e32 v67, 0.15915494, v67
	v_sin_f32_e32 v68, v60
	v_sin_f32_e32 v69, v61
	v_sin_f32_e32 v70, v62
	v_sin_f32_e32 v71, v63
	v_sin_f32_e32 v72, v64
	v_sin_f32_e32 v73, v65
	v_sin_f32_e32 v76, v66
	v_sin_f32_e32 v77, v67
	v_cos_f32_e32 v60, v60
	v_cos_f32_e32 v61, v61
	v_cos_f32_e32 v62, v62
	v_cos_f32_e32 v63, v63
	v_cos_f32_e32 v64, v64
	v_cos_f32_e32 v65, v65
	v_cos_f32_e32 v66, v66
	v_cos_f32_e32 v67, v67
	s_nop 0
	v_mul_f32_e32 v171, v68, v34
	v_mul_f32_e32 v172, v60, v34
	v_fmac_f32_e32 v172, v68, v24
	v_fma_f32 v24, v60, v24, -v171
	v_mov_b32_e32 v34, v172
	v_mul_f32_e32 v171, v69, v35
	v_mul_f32_e32 v172, v61, v35
	v_fmac_f32_e32 v172, v69, v25
	v_fma_f32 v25, v61, v25, -v171
	v_mov_b32_e32 v35, v172
	v_mul_f32_e32 v171, v70, v36
	v_mul_f32_e32 v172, v62, v36
	v_fmac_f32_e32 v172, v70, v26
	v_fma_f32 v26, v62, v26, -v171
	v_mov_b32_e32 v36, v172
	v_mul_f32_e32 v171, v71, v37
	v_mul_f32_e32 v172, v63, v37
	v_fmac_f32_e32 v172, v71, v27
	v_fma_f32 v27, v63, v27, -v171
	v_mov_b32_e32 v37, v172
	v_mul_f32_e32 v171, v72, v38
	v_mul_f32_e32 v172, v64, v38
	v_fmac_f32_e32 v172, v72, v28
	v_fma_f32 v28, v64, v28, -v171
	v_mov_b32_e32 v38, v172
	v_mul_f32_e32 v171, v73, v39
	v_mul_f32_e32 v172, v65, v39
	v_fmac_f32_e32 v172, v73, v29
	v_fma_f32 v29, v65, v29, -v171
	v_mov_b32_e32 v39, v172
	v_mul_f32_e32 v171, v76, v40
	v_mul_f32_e32 v172, v66, v40
	v_fmac_f32_e32 v172, v76, v30
	v_fma_f32 v30, v66, v30, -v171
	v_mov_b32_e32 v40, v172
	v_mul_f32_e32 v171, v77, v41
	v_mul_f32_e32 v172, v67, v41
	v_fmac_f32_e32 v172, v77, v31
	v_fma_f32 v31, v67, v31, -v171
	v_mov_b32_e32 v41, v172
	v_cvt_pk_bf16_f32 v110, v24, v25
	v_cvt_pk_bf16_f32 v111, v26, v27
	v_cvt_pk_bf16_f32 v112, v28, v29
	v_cvt_pk_bf16_f32 v113, v30, v31
	v_cvt_pk_bf16_f32 v102, v34, v35
	v_cvt_pk_bf16_f32 v103, v36, v37
	v_cvt_pk_bf16_f32 v104, v38, v39
	v_cvt_pk_bf16_f32 v105, v40, v41
	v_lshlrev_b32_e32 v24, 16, v106
	v_and_b32_e32 v25, 0xffff0000, v106
	v_lshlrev_b32_e32 v26, 16, v107
	v_and_b32_e32 v27, 0xffff0000, v107
	v_lshlrev_b32_e32 v28, 16, v108
	v_and_b32_e32 v29, 0xffff0000, v108
	v_lshlrev_b32_e32 v30, 16, v109
	v_and_b32_e32 v31, 0xffff0000, v109
	v_lshlrev_b32_e32 v34, 16, v98
	v_and_b32_e32 v35, 0xffff0000, v98
	v_lshlrev_b32_e32 v36, 16, v99
	v_and_b32_e32 v37, 0xffff0000, v99
	v_lshlrev_b32_e32 v38, 16, v100
	v_and_b32_e32 v39, 0xffff0000, v100
	v_lshlrev_b32_e32 v40, 16, v101
	v_and_b32_e32 v41, 0xffff0000, v101
	v_mul_f32_e32 v24, v24, v169
	v_mul_f32_e32 v25, v25, v169
	v_mul_f32_e32 v26, v26, v169
	v_mul_f32_e32 v27, v27, v169
	v_mul_f32_e32 v28, v28, v169
	v_mul_f32_e32 v29, v29, v169
	v_mul_f32_e32 v30, v30, v169
	v_mul_f32_e32 v31, v31, v169
	v_mul_f32_e32 v24, v24, v232
	v_mul_f32_e32 v25, v25, v233
	v_mul_f32_e32 v26, v26, v234
	v_mul_f32_e32 v27, v27, v235
	v_mul_f32_e32 v28, v28, v236
	v_mul_f32_e32 v29, v29, v237
	v_mul_f32_e32 v30, v30, v238
	v_mul_f32_e32 v31, v31, v239
	v_mul_f32_e32 v34, v34, v169
	v_mul_f32_e32 v35, v35, v169
	v_mul_f32_e32 v36, v36, v169
	v_mul_f32_e32 v37, v37, v169
	v_mul_f32_e32 v38, v38, v169
	v_mul_f32_e32 v39, v39, v169
	v_mul_f32_e32 v40, v40, v169
	v_mul_f32_e32 v41, v41, v169
	v_mul_f32_e32 v34, v34, v248
	v_mul_f32_e32 v35, v35, v249
	v_mul_f32_e32 v36, v36, v250
	v_mul_f32_e32 v37, v37, v251
	v_mul_f32_e32 v38, v38, v164
	v_mul_f32_e32 v39, v39, v165
	v_mul_f32_e32 v40, v40, v166
	v_mul_f32_e32 v41, v41, v167
	v_mul_f32_e32 v60, v86, v95
	v_mul_f32_e32 v61, v87, v95
	v_mul_f32_e32 v62, v88, v95
	v_mul_f32_e32 v63, v89, v95
	v_mul_f32_e32 v64, v90, v95
	v_mul_f32_e32 v65, v91, v95
	v_mul_f32_e32 v66, v92, v95
	v_mul_f32_e32 v67, v93, v95
	v_mul_f32_e32 v68, 0.15915494, v60
	v_mul_f32_e32 v69, 0.15915494, v61
	v_mul_f32_e32 v70, 0.15915494, v62
	v_mul_f32_e32 v71, 0.15915494, v63
	v_mul_f32_e32 v72, 0.15915494, v64
	v_mul_f32_e32 v73, 0.15915494, v65
	v_mul_f32_e32 v76, 0.15915494, v66
	v_mul_f32_e32 v77, 0.15915494, v67
	v_rndne_f32_e32 v68, v68
	v_rndne_f32_e32 v69, v69
	v_rndne_f32_e32 v70, v70
	v_rndne_f32_e32 v71, v71
	v_rndne_f32_e32 v72, v72
	v_rndne_f32_e32 v73, v73
	v_rndne_f32_e32 v76, v76
	v_rndne_f32_e32 v77, v77
	v_fmac_f32_e32 v60, 0xc0c90fdb, v68
	v_fmac_f32_e32 v61, 0xc0c90fdb, v69
	v_fmac_f32_e32 v62, 0xc0c90fdb, v70
	v_fmac_f32_e32 v63, 0xc0c90fdb, v71
	v_fmac_f32_e32 v64, 0xc0c90fdb, v72
	v_fmac_f32_e32 v65, 0xc0c90fdb, v73
	v_fmac_f32_e32 v66, 0xc0c90fdb, v76
	v_fmac_f32_e32 v67, 0xc0c90fdb, v77
	v_fmac_f32_e32 v60, 0x343bbd2e, v68
	v_fmac_f32_e32 v61, 0x343bbd2e, v69
	v_fmac_f32_e32 v62, 0x343bbd2e, v70
	v_fmac_f32_e32 v63, 0x343bbd2e, v71
	v_fmac_f32_e32 v64, 0x343bbd2e, v72
	v_fmac_f32_e32 v65, 0x343bbd2e, v73
	v_fmac_f32_e32 v66, 0x343bbd2e, v76
	v_fmac_f32_e32 v67, 0x343bbd2e, v77
	v_mul_f32_e32 v60, 0.15915494, v60
	v_mul_f32_e32 v61, 0.15915494, v61
	v_mul_f32_e32 v62, 0.15915494, v62
	v_mul_f32_e32 v63, 0.15915494, v63
	v_mul_f32_e32 v64, 0.15915494, v64
	v_mul_f32_e32 v65, 0.15915494, v65
	v_mul_f32_e32 v66, 0.15915494, v66
	v_mul_f32_e32 v67, 0.15915494, v67
	v_sin_f32_e32 v68, v60
	v_sin_f32_e32 v69, v61
	v_sin_f32_e32 v70, v62
	v_sin_f32_e32 v71, v63
	v_sin_f32_e32 v72, v64
	v_sin_f32_e32 v73, v65
	v_sin_f32_e32 v76, v66
	v_sin_f32_e32 v77, v67
	v_cos_f32_e32 v60, v60
	v_cos_f32_e32 v61, v61
	v_cos_f32_e32 v62, v62
	v_cos_f32_e32 v63, v63
	v_cos_f32_e32 v64, v64
	v_cos_f32_e32 v65, v65
	v_cos_f32_e32 v66, v66
	v_cos_f32_e32 v67, v67
	s_nop 0
	v_mul_f32_e32 v171, v68, v34
	v_mul_f32_e32 v172, v60, v34
	v_fmac_f32_e32 v172, v68, v24
	v_fma_f32 v24, v60, v24, -v171
	v_mov_b32_e32 v34, v172
	v_mul_f32_e32 v171, v69, v35
	v_mul_f32_e32 v172, v61, v35
	v_fmac_f32_e32 v172, v69, v25
	v_fma_f32 v25, v61, v25, -v171
	v_mov_b32_e32 v35, v172
	v_mul_f32_e32 v171, v70, v36
	v_mul_f32_e32 v172, v62, v36
	v_fmac_f32_e32 v172, v70, v26
	v_fma_f32 v26, v62, v26, -v171
	v_mov_b32_e32 v36, v172
	v_mul_f32_e32 v171, v71, v37
	v_mul_f32_e32 v172, v63, v37
	v_fmac_f32_e32 v172, v71, v27
	v_fma_f32 v27, v63, v27, -v171
	v_mov_b32_e32 v37, v172
	v_mul_f32_e32 v171, v72, v38
	v_mul_f32_e32 v172, v64, v38
	v_fmac_f32_e32 v172, v72, v28
	v_fma_f32 v28, v64, v28, -v171
	v_mov_b32_e32 v38, v172
	v_mul_f32_e32 v171, v73, v39
	v_mul_f32_e32 v172, v65, v39
	v_fmac_f32_e32 v172, v73, v29
	v_fma_f32 v29, v65, v29, -v171
	v_mov_b32_e32 v39, v172
	v_mul_f32_e32 v171, v76, v40
	v_mul_f32_e32 v172, v66, v40
	v_fmac_f32_e32 v172, v76, v30
	v_fma_f32 v30, v66, v30, -v171
	v_mov_b32_e32 v40, v172
	v_mul_f32_e32 v171, v77, v41
	v_mul_f32_e32 v172, v67, v41
	v_fmac_f32_e32 v172, v77, v31
	v_fma_f32 v31, v67, v31, -v171
	v_mov_b32_e32 v41, v172
	v_cvt_pk_bf16_f32 v106, v24, v25
	v_cvt_pk_bf16_f32 v107, v26, v27
	v_cvt_pk_bf16_f32 v108, v28, v29
	v_cvt_pk_bf16_f32 v109, v30, v31
	v_cvt_pk_bf16_f32 v98, v34, v35
	v_cvt_pk_bf16_f32 v99, v36, v37
	v_cvt_pk_bf16_f32 v100, v38, v39
	v_cvt_pk_bf16_f32 v101, v40, v41
	v_lshlrev_b32_e32 v12, 8, v187
	v_and_b32_e32 v13, 0x70, v53
	v_bitop3_b32 v0, v96, v12, v13 bitop3:0xde
	v_add_u32_e32 v196, 0, v0
	s_waitcnt lgkmcnt(0)
	s_barrier
	ds_read_b128 v[0:3], v196 offset:32768
	ds_read_b128 v[4:7], v196 offset:40960
	s_waitcnt vmcnt(7) lgkmcnt(1)
	v_mfma_f32_32x32x16_bf16 v[16:31], v[0:3], v[118:121], 0
	v_or_b32_e32 v0, 32, v96
	v_bitop3_b32 v0, v0, v12, v13 bitop3:0xde
	v_add_u32_e32 v201, 0, v0
	v_and_b32_e32 v15, 0xc0, v53
	v_lshlrev_b32_e32 v14, 3, v75
	s_mov_b32 s72, s73
	s_mov_b32 s74, s73
	s_waitcnt lgkmcnt(0)
	v_mfma_f32_32x32x16_bf16 v[32:47], v[4:7], v[118:121], 0
	ds_read_b128 v[0:3], v201 offset:32768
	ds_read_b128 v[4:7], v201 offset:40960
	s_mov_b32 s75, s73
	s_mov_b32 s76, s73
	s_mov_b32 s77, s73
	s_mov_b32 s78, s73
	s_mov_b32 s79, s73
	s_mov_b32 s80, s73
	s_waitcnt vmcnt(6) lgkmcnt(1)
	v_mfma_f32_32x32x16_bf16 v[16:31], v[0:3], v[114:117], v[16:31]
	v_or_b32_e32 v0, 64, v96
	v_bitop3_b32 v0, v0, v12, v13 bitop3:0xde
	v_add_u32_e32 v200, 0, v0
	s_mov_b32 s81, s73
	s_mov_b32 s82, s73
	s_mov_b32 s83, s73
	s_mov_b32 s84, s73
	s_waitcnt lgkmcnt(0)
	v_mfma_f32_32x32x16_bf16 v[32:47], v[4:7], v[114:117], v[32:47]
	ds_read_b128 v[0:3], v200 offset:32768
	ds_read_b128 v[4:7], v200 offset:40960
	s_mov_b32 s85, s73
	s_mov_b32 s86, s73
	s_mov_b32 s87, s73
	v_mov_b32_e32 v222, 9
	s_mov_b32 s3, 1
	v_mov_b32_e32 v189, 0
	s_waitcnt vmcnt(5) lgkmcnt(1)
	v_mfma_f32_32x32x16_bf16 v[16:31], v[0:3], v[126:129], v[16:31]
	v_or_b32_e32 v0, 0x60, v96
	v_bitop3_b32 v0, v0, v12, v13 bitop3:0xde
	v_add_u32_e32 v199, 0, v0
	s_waitcnt lgkmcnt(0)
	v_mfma_f32_32x32x16_bf16 v[32:47], v[4:7], v[126:129], v[32:47]
	ds_read_b128 v[0:3], v199 offset:32768
	ds_read_b128 v[4:7], v199 offset:40960
	s_waitcnt vmcnt(4) lgkmcnt(1)
	v_mfma_f32_32x32x16_bf16 v[16:31], v[0:3], v[122:125], v[16:31]
	v_or_b32_e32 v0, 0x80, v96
	v_bitop3_b32 v0, v0, v12, v13 bitop3:0xde
	v_add_u32_e32 v198, 0, v0
	s_waitcnt lgkmcnt(0)
	v_mfma_f32_32x32x16_bf16 v[32:47], v[4:7], v[122:125], v[32:47]
	ds_read_b128 v[0:3], v198 offset:32768
	ds_read_b128 v[4:7], v198 offset:40960
	s_waitcnt vmcnt(3) lgkmcnt(1)
	v_mfma_f32_32x32x16_bf16 v[16:31], v[0:3], v[110:113], v[16:31]
	v_or_b32_e32 v0, 0xa0, v96
	v_bitop3_b32 v0, v0, v12, v13 bitop3:0xde
	v_add_u32_e32 v197, 0, v0
	ds_read_b128 v[0:3], v197 offset:32768
	s_waitcnt lgkmcnt(1)
	v_mfma_f32_32x32x16_bf16 v[32:47], v[4:7], v[110:113], v[32:47]
	v_and_b32_e32 v4, 0x3fffffc0, v74
	v_lshl_add_u32 v183, v4, 2, s5
	ds_read_b128 v[4:7], v197 offset:40960
	s_cselect_b32 s5, 0, 0
	v_lshl_add_u32 v188, v187, 2, v183
	s_waitcnt vmcnt(2) lgkmcnt(1)
	v_mfma_f32_32x32x16_bf16 v[16:31], v[0:3], v[106:109], v[16:31]
	v_lshl_add_u64 v[0:1], v[50:51], 0, s[10:11]
	s_mov_b64 s[10:11], 0x6000
	v_lshl_add_u64 v[2:3], s[40:41], 0, v[0:1]
	v_lshl_add_u64 v[8:9], v[50:51], 0, s[10:11]
	v_lshl_add_u64 v[0:1], s[48:49], 0, v[0:1]
	v_lshl_add_u64 v[10:11], s[40:41], 0, v[8:9]
	global_load_dwordx4 v[52:55], v[2:3], off
	global_load_dwordx4 v[56:59], v[10:11], off
	v_lshl_add_u64 v[2:3], s[48:49], 0, v[8:9]
	global_load_dwordx4 v[60:63], v[0:1], off
	global_load_dwordx4 v[64:67], v[2:3], off
	v_or_b32_e32 v0, 0xc0, v96
	v_bitop3_b32 v0, v0, v12, v13 bitop3:0xde
	v_add_u32_e32 v203, 0, v0
	ds_read_b128 v[0:3], v203 offset:32768
	v_lshlrev_b32_e32 v9, 1, v74
	v_and_or_b32 v8, v14, 24, v15
	s_waitcnt lgkmcnt(1)
	v_mfma_f32_32x32x16_bf16 v[32:47], v[4:7], v[106:109], v[32:47]
	v_and_b32_e32 v4, 32, v9
	v_and_b32_e32 v5, 0x100, v14
	v_or3_b32 v76, v8, v4, v5
	ds_read_b128 v[4:7], v203 offset:40960
	s_mov_b64 s[10:11], 0xa000
	v_add_u32_e32 v191, s5, v76
	s_waitcnt vmcnt(5) lgkmcnt(1)
	v_mfma_f32_32x32x16_bf16 v[16:31], v[0:3], v[102:105], v[16:31]
	v_or_b32_e32 v0, 0xe0, v96
	v_bitop3_b32 v0, v0, v12, v13 bitop3:0xde
	v_add_u32_e32 v202, 0, v0
	ds_read_b128 v[0:3], v202 offset:32768
	ds_read_b128 v[68:71], v202 offset:40960
	s_waitcnt lgkmcnt(2)
	v_mfma_f32_32x32x16_bf16 v[32:47], v[4:7], v[102:105], v[32:47]
	s_waitcnt vmcnt(4) lgkmcnt(1)
	v_mfma_f32_32x32x16_bf16 v[16:31], v[0:3], v[98:101], v[16:31]
	v_mov_b64_e32 v[0:1], s[72:73]
	v_mov_b64_e32 v[14:15], s[86:87]
	v_mov_b64_e32 v[2:3], s[74:75]
	v_mov_b64_e32 v[4:5], s[76:77]
	v_mov_b64_e32 v[6:7], s[78:79]
	v_mov_b64_e32 v[8:9], s[80:81]
	v_mov_b64_e32 v[10:11], s[82:83]
	s_waitcnt lgkmcnt(0)
	v_mfma_f32_32x32x16_bf16 v[32:47], v[68:71], v[98:101], v[32:47]
	s_nop 2
	v_max_f32_e32 v68, v17, v17
	v_max_f32_e32 v69, v16, v16
	v_max_f32_e32 v68, v69, v68
	v_max3_f32 v68, v68, v18, v19
	v_max3_f32 v68, v68, v20, v21
	v_max3_f32 v68, v68, v22, v23
	v_max3_f32 v68, v68, v24, v25
	v_max3_f32 v68, v68, v26, v27
	v_max3_f32 v68, v68, v28, v29
	v_max3_f32 v68, v68, v30, v31
	v_max3_f32 v68, v68, v32, v33
	v_max3_f32 v68, v68, v34, v35
	v_max3_f32 v68, v68, v36, v37
	v_max3_f32 v68, v68, v38, v39
	v_max3_f32 v68, v68, v40, v41
	v_max3_f32 v68, v68, v42, v43
	v_max3_f32 v68, v68, v44, v45
	v_max3_f32 v77, v68, v46, v47
	v_lshl_add_u64 v[68:69], v[50:51], 0, s[10:11]
	v_lshl_add_u64 v[70:71], s[48:49], 0, v[68:69]
	v_lshl_add_u64 v[50:51], v[50:51], 0, s[12:13]
	v_lshl_add_u64 v[68:69], s[40:41], 0, v[68:69]
	v_lshl_add_u64 v[72:73], s[48:49], 0, v[50:51]
	global_load_dwordx4 v[138:141], v[70:71], off
	global_load_dwordx4 v[130:133], v[72:73], off
	v_lshl_add_u64 v[50:51], s[40:41], 0, v[50:51]
	global_load_dwordx4 v[142:145], v[68:69], off
	global_load_dwordx4 v[134:137], v[50:51], off
	v_mov_b32_e32 v78, v77
	s_nop 1
	v_permlane32_swap_b32_e32 v77, v78
	v_max_f32_e32 v50, v78, v78
	v_max_f32_e32 v51, v77, v77
	v_max_f32_e32 v50, v51, v50
	v_add_f32_e32 v51, 0x7149f2ca, v50
	v_cmp_ge_f32_e32 vcc, s35, v51
	s_cmp_eq_u64 vcc, exec
	v_max_f32_e32 v50, 0xf149f2ca, v50
	s_cselect_b64 vcc, -1, 0
	v_cndmask_b32_e32 v170, v50, v206, vcc
	v_sub_f32_e32 v51, 0xf149f2ca, v50
	v_mul_f32_e32 v50, 0xbe0293ee, v170
	v_fmamk_f32 v16, v16, 0x3e0293ee, v50
	v_exp_f32_e32 v163, v16
	v_fmamk_f32 v16, v17, 0x3e0293ee, v50
	v_exp_f32_e32 v177, v16
	v_fmamk_f32 v16, v18, 0x3e0293ee, v50
	v_exp_f32_e32 v164, v16
	v_fmamk_f32 v16, v19, 0x3e0293ee, v50
	v_exp_f32_e32 v227, v16
	v_fmamk_f32 v16, v20, 0x3e0293ee, v50
	v_exp_f32_e32 v176, v16
	v_fmamk_f32 v16, v21, 0x3e0293ee, v50
	v_exp_f32_e32 v230, v16
	v_fmamk_f32 v16, v22, 0x3e0293ee, v50
	v_exp_f32_e32 v165, v16
	v_fmamk_f32 v16, v23, 0x3e0293ee, v50
	v_exp_f32_e32 v175, v16
	v_fmamk_f32 v16, v24, 0x3e0293ee, v50
	v_mul_f32_e32 v51, 0x3e0293ee, v51
	v_exp_f32_e32 v166, v16
	v_fmamk_f32 v16, v25, 0x3e0293ee, v50
	v_exp_f32_e32 v51, v51
	v_exp_f32_e32 v173, v16
	v_fmamk_f32 v16, v26, 0x3e0293ee, v50
	v_exp_f32_e32 v167, v16
	v_fmamk_f32 v16, v27, 0x3e0293ee, v50
	v_exp_f32_e32 v174, v16
	v_fmamk_f32 v16, v28, 0x3e0293ee, v50
	s_addk_i32 s5, 0x4000
	s_mul_i32 s10, s42, 0x220000
	v_exp_f32_e32 v168, v16
	v_fmamk_f32 v16, v29, 0x3e0293ee, v50
	v_add_u32_e32 v190, s5, v76
	s_mul_hi_i32 s5, s42, 0x220000
	s_add_u32 s4, s10, s4
	v_pk_fma_f32 v[146:147], v[46:47], s[14:15], v[50:51] op_sel_hi:[1,0,0]
	v_pk_fma_f32 v[152:153], v[44:45], s[14:15], v[50:51] op_sel_hi:[1,0,0]
	v_pk_fma_f32 v[156:157], v[42:43], s[14:15], v[50:51] op_sel_hi:[1,0,0]
	v_pk_fma_f32 v[148:149], v[40:41], s[14:15], v[50:51] op_sel_hi:[1,0,0]
	v_pk_fma_f32 v[150:151], v[38:39], s[14:15], v[50:51] op_sel_hi:[1,0,0]
	v_pk_fma_f32 v[154:155], v[36:37], s[14:15], v[50:51] op_sel_hi:[1,0,0]
	v_pk_fma_f32 v[158:159], v[34:35], s[14:15], v[50:51] op_sel_hi:[1,0,0]
	v_pk_fma_f32 v[160:161], v[32:33], s[14:15], v[50:51] op_sel_hi:[1,0,0]
	v_exp_f32_e32 v171, v16
	v_fmamk_f32 v16, v30, 0x3e0293ee, v50
	v_fmac_f32_e32 v50, 0x3e0293ee, v31
	s_addc_u32 s5, s5, 0
	v_exp_f32_e32 v169, v16
	v_exp_f32_e32 v172, v50
	v_lshl_add_u64 v[16:17], s[4:5], 0, v[48:49]
	v_and_b32_e32 v18, 15, v74
	s_waitcnt vmcnt(4)
	v_lshl_or_b32 v16, v18, 4, v16
	v_mov_b64_e32 v[12:13], s[84:85]
	s_waitcnt vmcnt(7)
	ds_write_b128 v192, v[52:55] offset:16384
	s_waitcnt vmcnt(6)
	ds_write_b128 v193, v[56:59] offset:16384
	s_waitcnt vmcnt(5)
	ds_write_b128 v194, v[60:63] offset:49152
	s_waitcnt vmcnt(4)
	ds_write_b128 v195, v[64:67] offset:49152
	v_cndmask_b32_e64 v223, v51, 1.0, vcc
	v_lshl_add_u64 v[184:185], s[46:47], 0, v[16:17]
	v_mov_b64_e32 v[62:63], v[14:15]
	v_mov_b64_e32 v[46:47], v[14:15]
	v_mov_b64_e32 v[30:31], v[14:15]
	v_cmp_gt_u32_e64 s[40:41], 32, v75
	v_mov_b64_e32 v[60:61], v[12:13]
	v_mov_b64_e32 v[58:59], v[10:11]
	v_mov_b64_e32 v[56:57], v[8:9]
	v_mov_b64_e32 v[54:55], v[6:7]
	v_mov_b64_e32 v[52:53], v[4:5]
	v_mov_b64_e32 v[50:51], v[2:3]
	v_mov_b64_e32 v[48:49], v[0:1]
	v_mov_b64_e32 v[44:45], v[12:13]
	v_mov_b64_e32 v[42:43], v[10:11]
	v_mov_b64_e32 v[40:41], v[8:9]
	v_mov_b64_e32 v[38:39], v[6:7]
	v_mov_b64_e32 v[36:37], v[4:5]
	v_mov_b64_e32 v[34:35], v[2:3]
	v_mov_b64_e32 v[32:33], v[0:1]
	v_mov_b64_e32 v[28:29], v[12:13]
	v_mov_b64_e32 v[26:27], v[10:11]
	v_mov_b64_e32 v[24:25], v[8:9]
	v_mov_b64_e32 v[22:23], v[6:7]
	v_mov_b64_e32 v[20:21], v[4:5]
	v_mov_b64_e32 v[18:19], v[2:3]
	v_mov_b64_e32 v[16:17], v[0:1]
	s_waitcnt lgkmcnt(0)
	s_barrier
	v_lshlrev_b32_e32 v252, 6, v204
	v_add_u32_e32 v252, 0x12000, v252
	ds_write_b128 v252, v[178:181]
	ds_write_b128 v252, v[204:207] offset:16
	ds_write_b128 v252, v[208:211] offset:32
	ds_write_b128 v252, v[212:215] offset:48
.LBB0_910:
	ds_read_b128 v[64:67], v196 offset:49152
	ds_read_b128 v[68:71], v196 offset:57344
	ds_read_b128 v[232:235], v201 offset:49152
	ds_read_b128 v[236:239], v201 offset:57344
	v_add_f32_e32 v162, 0, v163
	v_add_f32_e32 v162, v177, v162
	s_waitcnt lgkmcnt(3)
	v_mfma_f32_32x32x16_bf16 v[80:95], v[64:67], v[118:121], 0
	v_add_f32_e32 v162, v164, v162
	v_add_f32_e32 v162, v227, v162
	v_add_f32_e32 v162, v176, v162
	v_add_f32_e32 v162, v230, v162
	v_add_f32_e32 v162, v165, v162
	v_add_f32_e32 v162, v175, v162
	v_add_f32_e32 v162, v166, v162
	s_waitcnt lgkmcnt(2)
	v_mfma_f32_32x32x16_bf16 v[64:79], v[68:71], v[118:121], 0
	v_add_f32_e32 v162, v173, v162
	v_add_f32_e32 v162, v167, v162
	v_add_f32_e32 v162, v174, v162
	v_exp_f32_e32 v160, v160
	v_add_f32_e32 v162, v168, v162
	v_exp_f32_e32 v161, v161
	v_add_f32_e32 v162, v171, v162
	s_waitcnt lgkmcnt(1)
	v_mfma_f32_32x32x16_bf16 v[80:95], v[232:235], v[114:117], v[80:95]
	v_exp_f32_e32 v158, v158
	v_add_f32_e32 v162, v169, v162
	v_exp_f32_e32 v159, v159
	v_add_f32_e32 v162, v172, v162
	v_exp_f32_e32 v154, v154
	v_add_f32_e32 v162, v160, v162
	v_exp_f32_e32 v155, v155
	s_waitcnt lgkmcnt(0)
	v_mfma_f32_32x32x16_bf16 v[64:79], v[236:239], v[114:117], v[64:79]
	ds_read_b128 v[232:235], v200 offset:49152
	ds_read_b128 v[236:239], v200 offset:57344
	v_add_f32_e32 v162, v161, v162
	v_exp_f32_e32 v150, v150
	v_add_f32_e32 v162, v158, v162
	v_exp_f32_e32 v151, v151
	v_add_f32_e32 v162, v159, v162
	v_exp_f32_e32 v148, v148
	s_waitcnt lgkmcnt(1)
	v_mfma_f32_32x32x16_bf16 v[80:95], v[232:235], v[126:129], v[80:95]
	v_add_f32_e32 v162, v154, v162
	v_exp_f32_e32 v149, v149
	v_add_f32_e32 v162, v155, v162
	v_exp_f32_e32 v156, v156
	v_add_f32_e32 v162, v150, v162
	v_exp_f32_e32 v157, v157
	v_add_f32_e32 v162, v151, v162
	s_waitcnt lgkmcnt(0)
	v_mfma_f32_32x32x16_bf16 v[64:79], v[236:239], v[126:129], v[64:79]
	ds_read_b128 v[232:235], v199 offset:49152
	ds_read_b128 v[236:239], v199 offset:57344
	v_exp_f32_e32 v152, v152
	v_add_f32_e32 v162, v148, v162
	v_exp_f32_e32 v153, v153
	v_add_f32_e32 v162, v149, v162
	v_exp_f32_e32 v146, v146
	v_add_f32_e32 v162, v156, v162
	s_waitcnt lgkmcnt(1)
	v_mfma_f32_32x32x16_bf16 v[80:95], v[232:235], v[122:125], v[80:95]
	v_exp_f32_e32 v147, v147
	v_add_f32_e32 v162, v157, v162
	v_add_f32_e32 v162, v152, v162
	v_add_f32_e32 v162, v153, v162
	v_add_f32_e32 v162, v146, v162
	v_add_f32_e32 v224, v147, v162
	v_mov_b32_e32 v225, v224
	s_waitcnt lgkmcnt(0)
	v_mfma_f32_32x32x16_bf16 v[64:79], v[236:239], v[122:125], v[64:79]
	ds_read_b128 v[232:235], v198 offset:49152
	ds_read_b128 v[236:239], v198 offset:57344
	v_permlane32_swap_b32_e32 v224, v225
	s_waitcnt lgkmcnt(1)
	v_mfma_f32_32x32x16_bf16 v[80:95], v[232:235], v[110:113], v[80:95]
	s_waitcnt lgkmcnt(0)
	v_mfma_f32_32x32x16_bf16 v[64:79], v[236:239], v[110:113], v[64:79]
	ds_read_b128 v[232:235], v197 offset:49152
	ds_read_b128 v[236:239], v197 offset:57344
	s_waitcnt lgkmcnt(1)
	v_mfma_f32_32x32x16_bf16 v[80:95], v[232:235], v[106:109], v[80:95]
	s_waitcnt lgkmcnt(0)
	v_mfma_f32_32x32x16_bf16 v[64:79], v[236:239], v[106:109], v[64:79]
	ds_read_b128 v[232:235], v203 offset:49152
	ds_read_b128 v[236:239], v203 offset:57344
	s_waitcnt lgkmcnt(1)
	v_mfma_f32_32x32x16_bf16 v[80:95], v[232:235], v[102:105], v[80:95]
	s_waitcnt lgkmcnt(0)
	v_mfma_f32_32x32x16_bf16 v[64:79], v[236:239], v[102:105], v[64:79]
	ds_read_b128 v[232:235], v202 offset:49152
	ds_read_b128 v[236:239], v202 offset:57344
	v_cvt_pk_bf16_f32 v162, v163, v177
	v_cvt_pk_bf16_f32 v163, v164, v227
	v_cvt_pk_bf16_f32 v164, v176, v230
	v_cvt_pk_bf16_f32 v165, v165, v175
	v_cvt_pk_bf16_f32 v166, v166, v173
	v_cvt_pk_bf16_f32 v167, v167, v174
	s_waitcnt lgkmcnt(1)
	v_mfma_f32_32x32x16_bf16 v[80:95], v[232:235], v[98:101], v[80:95]
	v_cvt_pk_bf16_f32 v168, v168, v171
	v_cvt_pk_bf16_f32 v169, v169, v172
	v_cvt_pk_bf16_f32 v172, v160, v161
	v_cvt_pk_bf16_f32 v173, v158, v159
	v_cvt_pk_bf16_f32 v174, v154, v155
	v_cvt_pk_bf16_f32 v175, v150, v151
	v_cvt_pk_bf16_f32 v226, v148, v149
	s_waitcnt lgkmcnt(0)
	v_mfma_f32_32x32x16_bf16 v[64:79], v[236:239], v[98:101], v[64:79]
	v_cvt_pk_bf16_f32 v227, v156, v157
	v_cvt_pk_bf16_f32 v228, v152, v153
	v_permlane32_swap_b32_e32 v162, v164
	v_cvt_pk_bf16_f32 v229, v146, v147
	v_permlane32_swap_b32_e32 v226, v228
	v_permlane32_swap_b32_e32 v163, v165
	v_permlane32_swap_b32_e32 v166, v168
	v_permlane32_swap_b32_e32 v167, v169
	v_permlane32_swap_b32_e32 v172, v174
	v_permlane32_swap_b32_e32 v173, v175
	v_permlane32_swap_b32_e32 v227, v229
	s_movk_i32 s4, 0xa000
	v_add_co_u32_e32 v146, vcc, s4, v184
	s_movk_i32 s4, 0xc000
	s_nop 0
	v_addc_co_u32_e32 v147, vcc, -1, v185, vcc
	v_add_co_u32_e32 v150, vcc, s4, v184
	s_mov_b32 s4, 0xffbba000
	s_nop 0
	v_addc_co_u32_e32 v151, vcc, -1, v185, vcc
	v_add_co_u32_e32 v154, vcc, s4, v184
	s_mov_b32 s4, 0xffbbc000
	s_nop 0
	v_addc_co_u32_e32 v155, vcc, -1, v185, vcc
	v_add_co_u32_e32 v158, vcc, s4, v184
	global_load_dwordx4 v[146:149], v[146:147], off
	s_nop 0
	global_load_dwordx4 v[150:153], v[150:151], off
	v_addc_co_u32_e32 v159, vcc, -1, v185, vcc
	global_load_dwordx4 v[154:157], v[154:155], off
	s_nop 0
	global_load_dwordx4 v[158:161], v[158:159], off
	ds_read_b64_tr_b16 v[230:231], v191 offset:0
	ds_read_b64_tr_b16 v[232:233], v191 offset:0x800
	ds_read_b64_tr_b16 v[234:235], v191 offset:0x1000
	ds_read_b64_tr_b16 v[236:237], v191 offset:0x1800
	ds_read_b64_tr_b16 v[238:239], v191 offset:0x2000
	ds_read_b64_tr_b16 v[240:241], v191 offset:0x2800
	ds_read_b64_tr_b16 v[242:243], v191 offset:0x3000
	ds_read_b64_tr_b16 v[244:245], v191 offset:0x3800
	ds_read_b64_tr_b16 v[178:179], v191 offset:0x200
	ds_read_b64_tr_b16 v[180:181], v191 offset:0xa00
	ds_read_b64_tr_b16 v[204:205], v191 offset:0x1200
	ds_read_b64_tr_b16 v[206:207], v191 offset:0x1a00
	ds_read_b64_tr_b16 v[208:209], v191 offset:0x2200
	ds_read_b64_tr_b16 v[210:211], v191 offset:0x2a00
	ds_read_b64_tr_b16 v[212:213], v191 offset:0x3200
	ds_read_b64_tr_b16 v[214:215], v191 offset:0x3a00
	s_waitcnt lgkmcnt(8)
	s_nop 0
	v_mfma_f32_32x32x16_bf16 v[0:15], v[162:165], v[230:233], v[0:15]
	v_mfma_f32_32x32x16_bf16 v[0:15], v[166:169], v[234:237], v[0:15]
	v_mfma_f32_32x32x16_bf16 v[0:15], v[172:175], v[238:241], v[0:15]
	v_mfma_f32_32x32x16_bf16 v[0:15], v[226:229], v[242:245], v[0:15]
	ds_read_b64_tr_b16 v[230:231], v191 offset:0x400
	ds_read_b64_tr_b16 v[232:233], v191 offset:0xc00
	ds_read_b64_tr_b16 v[234:235], v191 offset:0x1400
	ds_read_b64_tr_b16 v[236:237], v191 offset:0x1c00
	ds_read_b64_tr_b16 v[238:239], v191 offset:0x2400
	ds_read_b64_tr_b16 v[240:241], v191 offset:0x2c00
	ds_read_b64_tr_b16 v[242:243], v191 offset:0x3400
	ds_read_b64_tr_b16 v[244:245], v191 offset:0x3c00
	s_waitcnt lgkmcnt(8)
	v_mfma_f32_32x32x16_bf16 v[48:63], v[162:165], v[178:181], v[48:63]
	v_mfma_f32_32x32x16_bf16 v[48:63], v[166:169], v[204:207], v[48:63]
	v_mfma_f32_32x32x16_bf16 v[48:63], v[172:175], v[208:211], v[48:63]
	v_mfma_f32_32x32x16_bf16 v[48:63], v[226:229], v[212:215], v[48:63]
	ds_read_b64_tr_b16 v[178:179], v191 offset:0x600
	ds_read_b64_tr_b16 v[180:181], v191 offset:0xe00
	ds_read_b64_tr_b16 v[204:205], v191 offset:0x1600
	ds_read_b64_tr_b16 v[206:207], v191 offset:0x1e00
	ds_read_b64_tr_b16 v[208:209], v191 offset:0x2600
	ds_read_b64_tr_b16 v[210:211], v191 offset:0x2e00
	ds_read_b64_tr_b16 v[212:213], v191 offset:0x3600
	ds_read_b64_tr_b16 v[214:215], v191 offset:0x3e00
	s_waitcnt lgkmcnt(8)
	v_mfma_f32_32x32x16_bf16 v[32:47], v[162:165], v[230:233], v[32:47]
	v_mfma_f32_32x32x16_bf16 v[32:47], v[166:169], v[234:237], v[32:47]
	v_mfma_f32_32x32x16_bf16 v[32:47], v[172:175], v[238:241], v[32:47]
	v_mfma_f32_32x32x16_bf16 v[32:47], v[226:229], v[242:245], v[32:47]
	s_waitcnt lgkmcnt(0)
	v_mfma_f32_32x32x16_bf16 v[16:31], v[162:165], v[178:181], v[16:31]
	v_max_f32_e32 v162, v81, v81
	v_max_f32_e32 v163, v80, v80
	v_max_f32_e32 v162, v163, v162
	v_max3_f32 v162, v162, v82, v83
	v_max3_f32 v162, v162, v84, v85
	v_max3_f32 v162, v162, v86, v87
	v_max3_f32 v162, v162, v88, v89
	v_max3_f32 v162, v162, v90, v91
	v_max3_f32 v162, v162, v92, v93
	v_mfma_f32_32x32x16_bf16 v[16:31], v[166:169], v[204:207], v[16:31]
	v_max3_f32 v162, v162, v94, v95
	v_max3_f32 v162, v162, v64, v65
	v_max3_f32 v162, v162, v66, v67
	v_max3_f32 v162, v162, v68, v69
	v_max3_f32 v162, v162, v70, v71
	v_max3_f32 v162, v162, v72, v73
	v_max3_f32 v162, v162, v74, v75
	v_max3_f32 v162, v162, v76, v77
	v_mfma_f32_32x32x16_bf16 v[16:31], v[172:175], v[208:211], v[16:31]
	v_max3_f32 v162, v162, v78, v79
	v_mov_b32_e32 v163, v162
	s_nop 1
	v_permlane32_swap_b32_e32 v162, v163
	v_max_f32_e32 v163, v163, v163
	v_max_f32_e32 v162, v162, v162
	v_max_f32_e32 v162, v162, v163
	v_sub_f32_e32 v163, v162, v170
	v_cmp_ge_f32_e32 vcc, s35, v163
	v_max_f32_e32 v163, v170, v170
	v_max_f32_e32 v162, v163, v162
	v_mfma_f32_32x32x16_bf16 v[16:31], v[226:229], v[212:215], v[16:31]
	v_sub_f32_e32 v163, v170, v162
	v_mul_f32_e32 v163, 0x3e0293ee, v163
	v_exp_f32_e32 v163, v163
	s_cmp_eq_u64 vcc, exec
	s_cselect_b64 s[42:43], -1, 0
	s_barrier
	s_waitcnt vmcnt(4)
	v_cndmask_b32_e64 v226, v163, 1.0, s[42:43]
	v_cmp_gt_f32_e32 vcc, 1.0, v226
	s_waitcnt vmcnt(4)
	ds_write_b128 v192, v[134:137]
	ds_write_b128 v193, v[142:145]
	ds_write_b128 v194, v[130:133] offset:32768
	ds_write_b128 v195, v[138:141] offset:32768
	s_cbranch_vccz .LBB0_914
	s_and_saveexec_b64 s[48:49], s[40:41]
	ds_write_b32 v188, v226 offset:128
	s_or_b64 exec, exec, s[48:49]
	s_waitcnt lgkmcnt(0)
	v_add_u32_e32 v163, v183, v96
	ds_read_b128 v[164:167], v163 offset:224
	ds_read_b128 v[172:175], v163 offset:192
	ds_read_b128 v[228:231], v163 offset:160
	ds_read_b128 v[232:235], v163 offset:128
	s_waitcnt lgkmcnt(3)
	v_pk_mul_f32 v[12:13], v[12:13], v[164:165]
	s_waitcnt lgkmcnt(2)
	v_pk_mul_f32 v[8:9], v[8:9], v[172:173]
	s_waitcnt lgkmcnt(1)
	v_pk_mul_f32 v[4:5], v[4:5], v[228:229]
	v_pk_mul_f32 v[14:15], v[14:15], v[166:167]
	v_pk_mul_f32 v[10:11], v[10:11], v[174:175]
	v_pk_mul_f32 v[6:7], v[6:7], v[230:231]
	s_waitcnt lgkmcnt(0)
	v_pk_mul_f32 v[2:3], v[2:3], v[234:235]
	v_pk_mul_f32 v[0:1], v[0:1], v[232:233]
	v_pk_mul_f32 v[60:61], v[60:61], v[164:165]
	v_pk_mul_f32 v[56:57], v[56:57], v[172:173]
	v_pk_mul_f32 v[52:53], v[52:53], v[228:229]
	v_pk_mul_f32 v[62:63], v[62:63], v[166:167]
	v_pk_mul_f32 v[58:59], v[58:59], v[174:175]
	v_pk_mul_f32 v[54:55], v[54:55], v[230:231]
	v_pk_mul_f32 v[50:51], v[50:51], v[234:235]
	v_pk_mul_f32 v[48:49], v[48:49], v[232:233]
	v_pk_mul_f32 v[44:45], v[44:45], v[164:165]
	v_pk_mul_f32 v[40:41], v[40:41], v[172:173]
	v_pk_mul_f32 v[36:37], v[36:37], v[228:229]
	v_pk_mul_f32 v[46:47], v[46:47], v[166:167]
	v_pk_mul_f32 v[42:43], v[42:43], v[174:175]
	v_pk_mul_f32 v[38:39], v[38:39], v[230:231]
	v_pk_mul_f32 v[34:35], v[34:35], v[234:235]
	v_pk_mul_f32 v[32:33], v[32:33], v[232:233]
	v_pk_mul_f32 v[28:29], v[28:29], v[164:165]
	v_pk_mul_f32 v[24:25], v[24:25], v[172:173]
	v_pk_mul_f32 v[20:21], v[20:21], v[228:229]
	v_pk_mul_f32 v[30:31], v[30:31], v[166:167]
	v_pk_mul_f32 v[26:27], v[26:27], v[174:175]
	v_pk_mul_f32 v[22:23], v[22:23], v[230:231]
	v_pk_mul_f32 v[18:19], v[18:19], v[234:235]
	v_pk_mul_f32 v[16:17], v[16:17], v[232:233]

.LBB0_916:
	ds_read_b64_tr_b16 v[230:231], v190 offset:0
	ds_read_b64_tr_b16 v[232:233], v190 offset:0x800
	ds_read_b64_tr_b16 v[234:235], v190 offset:0x1000
	ds_read_b64_tr_b16 v[236:237], v190 offset:0x1800
	ds_read_b64_tr_b16 v[238:239], v190 offset:0x2000
	ds_read_b64_tr_b16 v[240:241], v190 offset:0x2800
	ds_read_b64_tr_b16 v[242:243], v190 offset:0x3000
	ds_read_b64_tr_b16 v[244:245], v190 offset:0x3800
	ds_read_b64_tr_b16 v[178:179], v190 offset:0x200
	ds_read_b64_tr_b16 v[180:181], v190 offset:0xa00
	ds_read_b64_tr_b16 v[204:205], v190 offset:0x1200
	ds_read_b64_tr_b16 v[206:207], v190 offset:0x1a00
	ds_read_b64_tr_b16 v[208:209], v190 offset:0x2200
	ds_read_b64_tr_b16 v[210:211], v190 offset:0x2a00
	ds_read_b64_tr_b16 v[212:213], v190 offset:0x3200
	ds_read_b64_tr_b16 v[214:215], v190 offset:0x3a00
	s_waitcnt lgkmcnt(8)
	s_nop 0
	v_mfma_f32_32x32x16_bf16 v[0:15], v[162:165], v[230:233], v[0:15]
	v_mfma_f32_32x32x16_bf16 v[0:15], v[166:169], v[234:237], v[0:15]
	v_mfma_f32_32x32x16_bf16 v[0:15], v[170:173], v[238:241], v[0:15]
	v_mfma_f32_32x32x16_bf16 v[0:15], v[174:177], v[242:245], v[0:15]
	ds_read_b64_tr_b16 v[230:231], v190 offset:0x400
	ds_read_b64_tr_b16 v[232:233], v190 offset:0xc00
	ds_read_b64_tr_b16 v[234:235], v190 offset:0x1400
	ds_read_b64_tr_b16 v[236:237], v190 offset:0x1c00
	ds_read_b64_tr_b16 v[238:239], v190 offset:0x2400
	ds_read_b64_tr_b16 v[240:241], v190 offset:0x2c00
	ds_read_b64_tr_b16 v[242:243], v190 offset:0x3400
	ds_read_b64_tr_b16 v[244:245], v190 offset:0x3c00
	s_waitcnt lgkmcnt(8)
	v_mfma_f32_32x32x16_bf16 v[48:63], v[162:165], v[178:181], v[48:63]
	v_mfma_f32_32x32x16_bf16 v[48:63], v[166:169], v[204:207], v[48:63]
	v_mfma_f32_32x32x16_bf16 v[48:63], v[170:173], v[208:211], v[48:63]
	v_mfma_f32_32x32x16_bf16 v[48:63], v[174:177], v[212:215], v[48:63]
	ds_read_b64_tr_b16 v[178:179], v190 offset:0x600
	ds_read_b64_tr_b16 v[180:181], v190 offset:0xe00
	ds_read_b64_tr_b16 v[204:205], v190 offset:0x1600
	ds_read_b64_tr_b16 v[206:207], v190 offset:0x1e00
	ds_read_b64_tr_b16 v[208:209], v190 offset:0x2600
	ds_read_b64_tr_b16 v[210:211], v190 offset:0x2e00
	ds_read_b64_tr_b16 v[212:213], v190 offset:0x3600
	ds_read_b64_tr_b16 v[214:215], v190 offset:0x3e00
	s_waitcnt lgkmcnt(8)
	v_mfma_f32_32x32x16_bf16 v[32:47], v[162:165], v[230:233], v[32:47]
	v_mfma_f32_32x32x16_bf16 v[32:47], v[166:169], v[234:237], v[32:47]
	v_mfma_f32_32x32x16_bf16 v[32:47], v[170:173], v[238:241], v[32:47]
	v_mfma_f32_32x32x16_bf16 v[32:47], v[174:177], v[242:245], v[32:47]
	s_waitcnt lgkmcnt(0)
	v_mfma_f32_32x32x16_bf16 v[16:31], v[162:165], v[178:181], v[16:31]
	v_max_f32_e32 v162, v81, v81
	v_max_f32_e32 v163, v80, v80
	v_max_f32_e32 v162, v163, v162
	v_max3_f32 v162, v162, v82, v83
	v_max3_f32 v162, v162, v84, v85
	v_max3_f32 v162, v162, v86, v87
	v_max3_f32 v162, v162, v88, v89
	v_max3_f32 v162, v162, v90, v91
	v_max3_f32 v162, v162, v92, v93
	v_mfma_f32_32x32x16_bf16 v[16:31], v[166:169], v[204:207], v[16:31]
	v_max3_f32 v162, v162, v94, v95
	v_max3_f32 v162, v162, v64, v65
	v_max3_f32 v162, v162, v66, v67
	v_max3_f32 v162, v162, v68, v69
	v_max3_f32 v162, v162, v70, v71
	v_max3_f32 v162, v162, v72, v73
	v_max3_f32 v162, v162, v74, v75
	v_max3_f32 v162, v162, v76, v77
	v_mfma_f32_32x32x16_bf16 v[16:31], v[170:173], v[208:211], v[16:31]
	v_max3_f32 v162, v162, v78, v79
	v_mov_b32_e32 v163, v162
	s_nop 1
	v_permlane32_swap_b32_e32 v162, v163
	v_max_f32_e32 v163, v163, v163
	v_max_f32_e32 v162, v162, v162
	v_max_f32_e32 v162, v162, v163
	v_sub_f32_e32 v163, v162, v227
	v_cmp_ge_f32_e32 vcc, s35, v163
	v_max_f32_e32 v163, v227, v227
	v_max_f32_e32 v163, v163, v162
	v_mfma_f32_32x32x16_bf16 v[16:31], v[174:177], v[212:215], v[16:31]
	v_sub_f32_e32 v162, v227, v163
	v_mul_f32_e32 v162, 0x3e0293ee, v162
	v_exp_f32_e32 v162, v162
	s_cmp_eq_u64 vcc, exec
	s_cselect_b64 s[42:43], -1, 0
	s_barrier
	s_waitcnt vmcnt(4)
	v_cndmask_b32_e64 v162, v162, 1.0, s[42:43]
	v_cmp_gt_f32_e32 vcc, 1.0, v162
	s_waitcnt vmcnt(3)
	ds_write_b128 v192, v[146:149] offset:16384
	s_waitcnt vmcnt(2)
	ds_write_b128 v193, v[150:153] offset:16384
	s_waitcnt vmcnt(1)
	ds_write_b128 v194, v[154:157] offset:49152
	s_waitcnt vmcnt(0)
	ds_write_b128 v195, v[158:161] offset:49152
	s_cbranch_vccz .LBB0_920
	s_and_saveexec_b64 s[50:51], s[40:41]
	ds_write_b32 v188, v162 offset:128
	s_or_b64 exec, exec, s[50:51]
	s_waitcnt lgkmcnt(0)
	v_add_u32_e32 v158, v183, v96
	ds_read_b128 v[146:149], v158 offset:224
	ds_read_b128 v[150:153], v158 offset:192
	ds_read_b128 v[154:157], v158 offset:160
	ds_read_b128 v[158:161], v158 offset:128
	s_waitcnt lgkmcnt(3)
	v_pk_mul_f32 v[12:13], v[12:13], v[146:147]
	s_waitcnt lgkmcnt(2)
	v_pk_mul_f32 v[8:9], v[8:9], v[150:151]
	s_waitcnt lgkmcnt(1)
	v_pk_mul_f32 v[4:5], v[4:5], v[154:155]
	v_pk_mul_f32 v[14:15], v[14:15], v[148:149]
	v_pk_mul_f32 v[10:11], v[10:11], v[152:153]
	v_pk_mul_f32 v[6:7], v[6:7], v[156:157]
	s_waitcnt lgkmcnt(0)
	v_pk_mul_f32 v[2:3], v[2:3], v[160:161]
	v_pk_mul_f32 v[0:1], v[0:1], v[158:159]
	v_pk_mul_f32 v[60:61], v[60:61], v[146:147]
	v_pk_mul_f32 v[56:57], v[56:57], v[150:151]
	v_pk_mul_f32 v[52:53], v[52:53], v[154:155]
	v_pk_mul_f32 v[62:63], v[62:63], v[148:149]
	v_pk_mul_f32 v[58:59], v[58:59], v[152:153]
	v_pk_mul_f32 v[54:55], v[54:55], v[156:157]
	v_pk_mul_f32 v[50:51], v[50:51], v[160:161]
	v_pk_mul_f32 v[48:49], v[48:49], v[158:159]
	v_pk_mul_f32 v[44:45], v[44:45], v[146:147]
	v_pk_mul_f32 v[40:41], v[40:41], v[150:151]
	v_pk_mul_f32 v[36:37], v[36:37], v[154:155]
	v_pk_mul_f32 v[46:47], v[46:47], v[148:149]
	v_pk_mul_f32 v[42:43], v[42:43], v[152:153]
	v_pk_mul_f32 v[38:39], v[38:39], v[156:157]
	v_pk_mul_f32 v[34:35], v[34:35], v[160:161]
	v_pk_mul_f32 v[32:33], v[32:33], v[158:159]
	v_pk_mul_f32 v[28:29], v[28:29], v[146:147]
	v_pk_mul_f32 v[24:25], v[24:25], v[150:151]
	v_pk_mul_f32 v[20:21], v[20:21], v[154:155]
	v_pk_mul_f32 v[30:31], v[30:31], v[148:149]
	v_pk_mul_f32 v[26:27], v[26:27], v[152:153]
	v_pk_mul_f32 v[22:23], v[22:23], v[156:157]
	v_pk_mul_f32 v[18:19], v[18:19], v[160:161]
	v_pk_mul_f32 v[16:17], v[16:17], v[158:159]

.LBB0_922:
	ds_read_b128 v[178:181], v252
	ds_read_b128 v[204:207], v252 offset:16
	ds_read_b128 v[208:211], v252 offset:32
	ds_read_b128 v[212:215], v252 offset:48
	s_waitcnt lgkmcnt(0)
	ds_read_b128 v[64:67], v196 offset:49152
	ds_read_b128 v[68:71], v196 offset:57344
	s_waitcnt lgkmcnt(1)
	v_mfma_f32_32x32x16_bf16 v[80:95], v[64:67], v[118:121], 0
	s_waitcnt lgkmcnt(0)
	v_mfma_f32_32x32x16_bf16 v[64:79], v[68:71], v[118:121], 0
	ds_read_b128 v[118:121], v201 offset:49152
	ds_read_b128 v[130:133], v201 offset:57344
	s_waitcnt lgkmcnt(1)
	v_mfma_f32_32x32x16_bf16 v[80:95], v[118:121], v[114:117], v[80:95]
	s_waitcnt lgkmcnt(0)
	v_mfma_f32_32x32x16_bf16 v[64:79], v[130:133], v[114:117], v[64:79]
	ds_read_b128 v[114:117], v200 offset:49152
	ds_read_b128 v[118:121], v200 offset:57344
	s_waitcnt lgkmcnt(1)
	v_mfma_f32_32x32x16_bf16 v[80:95], v[114:117], v[126:129], v[80:95]
	s_waitcnt lgkmcnt(0)
	v_mfma_f32_32x32x16_bf16 v[64:79], v[118:121], v[126:129], v[64:79]
	ds_read_b128 v[114:117], v199 offset:49152
	ds_read_b128 v[118:121], v199 offset:57344
	s_waitcnt lgkmcnt(1)
	v_mfma_f32_32x32x16_bf16 v[80:95], v[114:117], v[122:125], v[80:95]
	s_waitcnt lgkmcnt(0)
	v_mfma_f32_32x32x16_bf16 v[64:79], v[118:121], v[122:125], v[64:79]
	ds_read_b128 v[114:117], v198 offset:49152
	ds_read_b128 v[118:121], v198 offset:57344
	v_exp_f32_e32 v122, v146
	v_exp_f32_e32 v123, v147
	s_waitcnt lgkmcnt(1)
	v_mfma_f32_32x32x16_bf16 v[80:95], v[114:117], v[110:113], v[80:95]
	s_waitcnt lgkmcnt(0)
	v_mfma_f32_32x32x16_bf16 v[64:79], v[118:121], v[110:113], v[64:79]
	ds_read_b128 v[110:113], v197 offset:49152
	ds_read_b128 v[114:117], v197 offset:57344
	v_exp_f32_e32 v118, v156
	v_exp_f32_e32 v119, v157
	v_exp_f32_e32 v120, v152
	v_exp_f32_e32 v121, v153
	s_waitcnt lgkmcnt(1)
	v_mfma_f32_32x32x16_bf16 v[80:95], v[110:113], v[106:109], v[80:95]
	s_waitcnt lgkmcnt(0)
	v_mfma_f32_32x32x16_bf16 v[64:79], v[114:117], v[106:109], v[64:79]
	ds_read_b128 v[106:109], v203 offset:49152
	ds_read_b128 v[110:113], v203 offset:57344
	v_exp_f32_e32 v114, v150
	v_exp_f32_e32 v115, v151
	v_exp_f32_e32 v116, v148
	v_exp_f32_e32 v117, v149
	s_waitcnt lgkmcnt(1)
	v_mfma_f32_32x32x16_bf16 v[80:95], v[106:109], v[102:105], v[80:95]
	s_waitcnt lgkmcnt(0)
	v_mfma_f32_32x32x16_bf16 v[64:79], v[110:113], v[102:105], v[64:79]
	ds_read_b128 v[102:105], v202 offset:49152
	ds_read_b128 v[106:109], v202 offset:57344
	v_exp_f32_e32 v110, v158
	v_exp_f32_e32 v111, v159
	v_exp_f32_e32 v112, v154
	v_exp_f32_e32 v113, v155
	s_waitcnt lgkmcnt(1)
	v_mfma_f32_32x32x16_bf16 v[80:95], v[102:105], v[98:101], v[80:95]
	s_waitcnt lgkmcnt(0)
	v_mfma_f32_32x32x16_bf16 v[64:79], v[106:109], v[98:101], v[64:79]
	v_add_f32_e32 v98, 0, v163
	v_add_f32_e32 v98, v177, v98
	v_add_f32_e32 v98, v164, v98
	v_add_f32_e32 v98, v227, v98
	v_add_f32_e32 v98, v176, v98
	v_add_f32_e32 v98, v230, v98
	v_add_f32_e32 v98, v165, v98
	v_add_f32_e32 v98, v175, v98
	v_add_f32_e32 v98, v166, v98
	v_add_f32_e32 v98, v173, v98
	v_add_f32_e32 v98, v167, v98
	v_add_f32_e32 v98, v174, v98
	v_exp_f32_e32 v108, v160
	v_add_f32_e32 v98, v168, v98
	v_exp_f32_e32 v109, v161
	v_add_f32_e32 v98, v171, v98
	v_add_f32_e32 v98, v169, v98
	v_add_f32_e32 v98, v172, v98
	v_add_f32_e32 v98, v108, v98
	v_add_f32_e32 v98, v109, v98
	v_add_f32_e32 v98, v110, v98
	v_add_f32_e32 v98, v111, v98
	v_add_f32_e32 v98, v112, v98
	v_add_f32_e32 v98, v113, v98
	v_add_f32_e32 v98, v114, v98
	v_add_f32_e32 v98, v115, v98
	v_add_f32_e32 v98, v116, v98
	v_add_f32_e32 v98, v117, v98
	v_add_f32_e32 v98, v118, v98
	v_add_f32_e32 v98, v119, v98
	v_add_f32_e32 v98, v120, v98
	v_add_f32_e32 v98, v121, v98
	v_add_f32_e32 v98, v122, v98
	v_add_f32_e32 v98, v123, v98
	v_mov_b32_e32 v99, v98
	v_cvt_pk_bf16_f32 v100, v163, v177
	v_cvt_pk_bf16_f32 v101, v164, v227
	v_cvt_pk_bf16_f32 v102, v176, v230
	v_cvt_pk_bf16_f32 v103, v165, v175
	s_nop 1
	v_permlane32_swap_b32_e32 v98, v99
	v_permlane32_swap_b32_e32 v100, v102
	v_permlane32_swap_b32_e32 v101, v103
	v_cvt_pk_bf16_f32 v104, v166, v173
	v_cvt_pk_bf16_f32 v105, v167, v174
	v_cvt_pk_bf16_f32 v106, v168, v171
	v_cvt_pk_bf16_f32 v107, v169, v172
	v_cvt_pk_bf16_f32 v108, v108, v109
	v_cvt_pk_bf16_f32 v109, v110, v111
	v_cvt_pk_bf16_f32 v110, v112, v113
	v_cvt_pk_bf16_f32 v111, v114, v115
	v_cvt_pk_bf16_f32 v112, v116, v117
	v_cvt_pk_bf16_f32 v113, v118, v119
	v_cvt_pk_bf16_f32 v114, v120, v121
	v_cvt_pk_bf16_f32 v115, v122, v123
	s_nop 0
	v_permlane32_swap_b32_e32 v104, v106
	v_permlane32_swap_b32_e32 v105, v107
	v_permlane32_swap_b32_e32 v108, v110
	v_permlane32_swap_b32_e32 v109, v111
	v_permlane32_swap_b32_e32 v112, v114
	v_permlane32_swap_b32_e32 v113, v115
	ds_read_b64_tr_b16 v[116:117], v191 offset:0
	ds_read_b64_tr_b16 v[118:119], v191 offset:0x800
	ds_read_b64_tr_b16 v[120:121], v191 offset:0x1000
	ds_read_b64_tr_b16 v[122:123], v191 offset:0x1800
	ds_read_b64_tr_b16 v[124:125], v191 offset:0x2000
	ds_read_b64_tr_b16 v[126:127], v191 offset:0x2800
	ds_read_b64_tr_b16 v[128:129], v191 offset:0x3000
	ds_read_b64_tr_b16 v[130:131], v191 offset:0x3800
	s_waitcnt lgkmcnt(0)
	s_nop 0
	v_mfma_f32_32x32x16_bf16 v[0:15], v[100:103], v[116:119], v[0:15]
	ds_read_b64_tr_b16 v[116:117], v191 offset:0x200
	ds_read_b64_tr_b16 v[118:119], v191 offset:0xa00
	v_mfma_f32_32x32x16_bf16 v[0:15], v[104:107], v[120:123], v[0:15]
	ds_read_b64_tr_b16 v[120:121], v191 offset:0x1200
	ds_read_b64_tr_b16 v[122:123], v191 offset:0x1a00
	v_mfma_f32_32x32x16_bf16 v[0:15], v[108:111], v[124:127], v[0:15]
	ds_read_b64_tr_b16 v[124:125], v191 offset:0x2200
	ds_read_b64_tr_b16 v[126:127], v191 offset:0x2a00
	v_mfma_f32_32x32x16_bf16 v[0:15], v[112:115], v[128:131], v[0:15]
	ds_read_b64_tr_b16 v[128:129], v191 offset:0x3200
	ds_read_b64_tr_b16 v[130:131], v191 offset:0x3a00
	s_waitcnt lgkmcnt(0)
	v_mfma_f32_32x32x16_bf16 v[48:63], v[100:103], v[116:119], v[48:63]
	ds_read_b64_tr_b16 v[116:117], v191 offset:0x400
	ds_read_b64_tr_b16 v[118:119], v191 offset:0xc00
	v_mfma_f32_32x32x16_bf16 v[48:63], v[104:107], v[120:123], v[48:63]
	ds_read_b64_tr_b16 v[120:121], v191 offset:0x1400
	ds_read_b64_tr_b16 v[122:123], v191 offset:0x1c00
	v_mfma_f32_32x32x16_bf16 v[48:63], v[108:111], v[124:127], v[48:63]
	ds_read_b64_tr_b16 v[124:125], v191 offset:0x2400
	ds_read_b64_tr_b16 v[126:127], v191 offset:0x2c00
	v_mfma_f32_32x32x16_bf16 v[48:63], v[112:115], v[128:131], v[48:63]
	ds_read_b64_tr_b16 v[128:129], v191 offset:0x3400
	ds_read_b64_tr_b16 v[130:131], v191 offset:0x3c00
	s_waitcnt lgkmcnt(0)
	v_mfma_f32_32x32x16_bf16 v[32:47], v[100:103], v[116:119], v[32:47]
	ds_read_b64_tr_b16 v[116:117], v191 offset:0x600
	ds_read_b64_tr_b16 v[118:119], v191 offset:0xe00
	v_mfma_f32_32x32x16_bf16 v[32:47], v[104:107], v[120:123], v[32:47]
	ds_read_b64_tr_b16 v[120:121], v191 offset:0x1600
	ds_read_b64_tr_b16 v[122:123], v191 offset:0x1e00
	v_mfma_f32_32x32x16_bf16 v[32:47], v[108:111], v[124:127], v[32:47]
	ds_read_b64_tr_b16 v[124:125], v191 offset:0x2600
	ds_read_b64_tr_b16 v[126:127], v191 offset:0x2e00
	v_mfma_f32_32x32x16_bf16 v[32:47], v[112:115], v[128:131], v[32:47]
	ds_read_b64_tr_b16 v[128:129], v191 offset:0x3600
	ds_read_b64_tr_b16 v[130:131], v191 offset:0x3e00
	s_waitcnt lgkmcnt(0)
	v_mfma_f32_32x32x16_bf16 v[16:31], v[100:103], v[116:119], v[16:31]
	v_max_f32_e32 v100, v81, v81
	v_max_f32_e32 v101, v80, v80
	v_max_f32_e32 v100, v101, v100
	v_max3_f32 v100, v100, v82, v83
	v_max3_f32 v100, v100, v84, v85
	v_max3_f32 v100, v100, v86, v87
	v_max3_f32 v100, v100, v88, v89
	v_max3_f32 v100, v100, v90, v91
	v_max3_f32 v100, v100, v92, v93
	v_mfma_f32_32x32x16_bf16 v[16:31], v[104:107], v[120:123], v[16:31]
	v_max3_f32 v100, v100, v94, v95
	v_max3_f32 v100, v100, v64, v65
	v_max3_f32 v100, v100, v66, v67
	v_max3_f32 v100, v100, v68, v69
	v_max3_f32 v100, v100, v70, v71
	v_max3_f32 v100, v100, v72, v73
	v_max3_f32 v100, v100, v74, v75
	v_max3_f32 v100, v100, v76, v77
	v_mfma_f32_32x32x16_bf16 v[16:31], v[108:111], v[124:127], v[16:31]
	v_max3_f32 v100, v100, v78, v79
	v_mov_b32_e32 v101, v100
	s_nop 1
	v_permlane32_swap_b32_e32 v100, v101
	v_max_f32_e32 v101, v101, v101
	v_max_f32_e32 v100, v100, v100
	v_max_f32_e32 v100, v100, v101
	v_sub_f32_e32 v101, v100, v170
	v_cmp_ge_f32_e32 vcc, s35, v101
	v_max_f32_e32 v101, v170, v170
	v_max_f32_e32 v101, v101, v100
	v_mfma_f32_32x32x16_bf16 v[16:31], v[112:115], v[128:131], v[16:31]
	v_sub_f32_e32 v100, v170, v101
	v_mul_f32_e32 v100, 0x3e0293ee, v100
	v_exp_f32_e32 v100, v100
	s_cmp_eq_u64 vcc, exec
	s_cselect_b64 s[42:43], -1, 0
	v_cndmask_b32_e64 v100, v100, 1.0, s[42:43]
	v_cmp_gt_f32_e32 vcc, 1.0, v100
	s_barrier
	s_cbranch_vccz .LBB0_926
	s_and_saveexec_b64 s[48:49], s[40:41]
	ds_write_b32 v188, v100 offset:128
	s_or_b64 exec, exec, s[48:49]
	s_waitcnt lgkmcnt(0)
	v_add_u32_e32 v114, v183, v96
	ds_read_b128 v[102:105], v114 offset:224
	ds_read_b128 v[106:109], v114 offset:192
	ds_read_b128 v[110:113], v114 offset:160
	ds_read_b128 v[114:117], v114 offset:128
	s_waitcnt lgkmcnt(3)
	v_pk_mul_f32 v[12:13], v[12:13], v[102:103]
	s_waitcnt lgkmcnt(2)
	v_pk_mul_f32 v[8:9], v[8:9], v[106:107]
	s_waitcnt lgkmcnt(1)
	v_pk_mul_f32 v[4:5], v[4:5], v[110:111]
	v_pk_mul_f32 v[14:15], v[14:15], v[104:105]
	v_pk_mul_f32 v[10:11], v[10:11], v[108:109]
	v_pk_mul_f32 v[6:7], v[6:7], v[112:113]
	s_waitcnt lgkmcnt(0)
	v_pk_mul_f32 v[2:3], v[2:3], v[116:117]
	v_pk_mul_f32 v[0:1], v[0:1], v[114:115]
	v_pk_mul_f32 v[60:61], v[60:61], v[102:103]
	v_pk_mul_f32 v[56:57], v[56:57], v[106:107]
	v_pk_mul_f32 v[52:53], v[52:53], v[110:111]
	v_pk_mul_f32 v[62:63], v[62:63], v[104:105]
	v_pk_mul_f32 v[58:59], v[58:59], v[108:109]
	v_pk_mul_f32 v[54:55], v[54:55], v[112:113]
	v_pk_mul_f32 v[50:51], v[50:51], v[116:117]
	v_pk_mul_f32 v[48:49], v[48:49], v[114:115]
	v_pk_mul_f32 v[44:45], v[44:45], v[102:103]
	v_pk_mul_f32 v[40:41], v[40:41], v[106:107]
	v_pk_mul_f32 v[36:37], v[36:37], v[110:111]
	v_pk_mul_f32 v[46:47], v[46:47], v[104:105]
	v_pk_mul_f32 v[42:43], v[42:43], v[108:109]
	v_pk_mul_f32 v[38:39], v[38:39], v[112:113]
	v_pk_mul_f32 v[34:35], v[34:35], v[116:117]
	v_pk_mul_f32 v[32:33], v[32:33], v[114:115]
	v_pk_mul_f32 v[28:29], v[28:29], v[102:103]
	v_pk_mul_f32 v[24:25], v[24:25], v[106:107]
	v_pk_mul_f32 v[20:21], v[20:21], v[110:111]
	v_pk_mul_f32 v[30:31], v[30:31], v[104:105]
	v_pk_mul_f32 v[26:27], v[26:27], v[108:109]
	v_pk_mul_f32 v[22:23], v[22:23], v[112:113]
	v_pk_mul_f32 v[18:19], v[18:19], v[116:117]
	v_pk_mul_f32 v[16:17], v[16:17], v[114:115]
